# GEMM K-loop weight (B) LDS-DMA loads non-temporal
# baseline (speedup 1.0000x reference)
.LBB0_246:
	s_add_u32 s3, s34, 0xfff80080
	s_addc_u32 s6, s35, -1
	s_add_i32 s7, 0, 0x10000
	s_cmp_eq_u32 s2, 28
	s_cselect_b32 s43, s15, s6
	s_cselect_b32 s42, s47, s3
	s_cselect_b32 s39, s13, s50
	s_cselect_b32 s38, s48, s49
	s_add_i32 s3, 0, 0x14000
	v_add_u32_e32 v156, s7, v145
	v_add_u32_e32 v172, s3, v145
	ds_read_b128 v[140:143], v156
	ds_read_b128 v[148:151], v156 offset:1024
	ds_read_b128 v[152:155], v156 offset:2048
	ds_read_b128 v[156:159], v156 offset:3072
	ds_read_b128 v[160:163], v172
	ds_read_b128 v[164:167], v172 offset:1024
	ds_read_b128 v[168:171], v172 offset:2048
	ds_read_b128 v[172:175], v172 offset:3072
	v_lshl_add_u64 v[176:177], s[34:35], 0, v[136:137]
	s_add_i32 m0, s18, 0xc000
	ds_read_b128 v[182:185], v147
	ds_read_b128 v[186:189], v147 offset:1024
	ds_read_b128 v[190:193], v147 offset:2048
	ds_read_b128 v[214:217], v147 offset:3072
	ds_read_b128 v[218:221], v147 offset:4096
	ds_read_b128 v[222:225], v147 offset:5120
	ds_read_b128 v[226:229], v147 offset:6144
	ds_read_b128 v[230:233], v147 offset:7168
	global_load_lds_dwordx4 v[176:177], off
	v_lshl_add_u64 v[176:177], s[34:35], 0, v[138:139]
	s_add_i32 m0, s18, 0xe000
	s_nop 0
	global_load_lds_dwordx4 v[176:177], off
	s_waitcnt vmcnt(8)
	s_waitcnt lgkmcnt(0)
	s_barrier
	s_setprio 1
	s_waitcnt lgkmcnt(0)
	v_mfma_f32_16x16x32_bf16 v[126:129], v[140:143], v[182:185], v[126:129]
	v_mfma_f32_16x16x32_bf16 v[122:125], v[152:155], v[182:185], v[122:125]
	v_mfma_f32_16x16x32_bf16 v[118:121], v[140:143], v[190:193], v[118:121]
	v_mfma_f32_16x16x32_bf16 v[110:113], v[152:155], v[190:193], v[110:113]
	v_mfma_f32_16x16x32_bf16 v[102:105], v[140:143], v[218:221], v[102:105]
	v_mfma_f32_16x16x32_bf16 v[92:95], v[152:155], v[218:221], v[92:95]
	v_mfma_f32_16x16x32_bf16 v[84:87], v[140:143], v[226:229], v[84:87]
	v_mfma_f32_16x16x32_bf16 v[76:79], v[152:155], v[226:229], v[76:79]
	v_mfma_f32_16x16x32_bf16 v[126:129], v[148:151], v[186:189], v[126:129]
	v_mfma_f32_16x16x32_bf16 v[122:125], v[156:159], v[186:189], v[122:125]
	v_mfma_f32_16x16x32_bf16 v[118:121], v[148:151], v[214:217], v[118:121]
	v_mfma_f32_16x16x32_bf16 v[110:113], v[156:159], v[214:217], v[110:113]
	v_mfma_f32_16x16x32_bf16 v[102:105], v[148:151], v[222:225], v[102:105]
	v_mfma_f32_16x16x32_bf16 v[92:95], v[156:159], v[222:225], v[92:95]
	v_mfma_f32_16x16x32_bf16 v[84:87], v[148:151], v[230:233], v[84:87]
	v_mfma_f32_16x16x32_bf16 v[76:79], v[156:159], v[230:233], v[76:79]
	s_setprio 0
	s_setprio 1
	v_mfma_f32_16x16x32_bf16 v[114:117], v[160:163], v[182:185], v[114:117]
	v_mfma_f32_16x16x32_bf16 v[106:109], v[168:171], v[182:185], v[106:109]
	v_mfma_f32_16x16x32_bf16 v[98:101], v[160:163], v[190:193], v[98:101]
	v_mfma_f32_16x16x32_bf16 v[88:91], v[168:171], v[190:193], v[88:91]
	v_mfma_f32_16x16x32_bf16 v[80:83], v[160:163], v[218:221], v[80:83]
	v_mfma_f32_16x16x32_bf16 v[72:75], v[168:171], v[218:221], v[72:75]
	v_mfma_f32_16x16x32_bf16 v[68:71], v[160:163], v[226:229], v[68:71]
	v_mfma_f32_16x16x32_bf16 v[64:67], v[168:171], v[226:229], v[64:67]
	v_mfma_f32_16x16x32_bf16 v[114:117], v[164:167], v[186:189], v[114:117]
	v_mfma_f32_16x16x32_bf16 v[106:109], v[172:175], v[186:189], v[106:109]
	v_mfma_f32_16x16x32_bf16 v[98:101], v[164:167], v[214:217], v[98:101]
	v_mfma_f32_16x16x32_bf16 v[88:91], v[172:175], v[214:217], v[88:91]
	v_mfma_f32_16x16x32_bf16 v[80:83], v[164:167], v[222:225], v[80:83]
	v_mfma_f32_16x16x32_bf16 v[72:75], v[172:175], v[222:225], v[72:75]
	v_mfma_f32_16x16x32_bf16 v[68:71], v[164:167], v[230:233], v[68:71]
	v_mfma_f32_16x16x32_bf16 v[64:67], v[172:175], v[230:233], v[64:67]
	s_setprio 0
	s_barrier
	s_add_i32 s6, s7, s17
	v_lshl_add_u64 v[176:177], s[38:39], 0, v[96:97]
	s_mov_b32 m0, s6
	ds_read_b128 v[182:185], v147 offset:16384
	ds_read_b128 v[186:189], v147 offset:17408
	ds_read_b128 v[190:193], v147 offset:18432
	ds_read_b128 v[214:217], v147 offset:19456
	ds_read_b128 v[218:221], v147 offset:20480
	ds_read_b128 v[222:225], v147 offset:21504
	ds_read_b128 v[226:229], v147 offset:22528
	ds_read_b128 v[230:233], v147 offset:23552
	global_load_lds_dwordx4 v[176:177], off nt
	s_add_i32 m0, s6, 0x2000
	s_add_u32 s6, s38, 0x80000
	v_lshl_add_u64 v[178:179], s[38:39], 0, v[130:131]
	s_addc_u32 s7, s39, 0
	s_add_i32 s3, s3, s17
	global_load_lds_dwordx4 v[178:179], off nt
	v_lshl_add_u64 v[180:181], s[6:7], 0, v[96:97]
	s_mov_b32 m0, s3
	v_lshl_add_u64 v[194:195], s[42:43], 0, v[132:133]
	global_load_lds_dwordx4 v[180:181], off nt
	v_lshl_add_u64 v[180:181], s[6:7], 0, v[130:131]
	s_add_i32 m0, s3, 0x2000
	s_nop 0
	global_load_lds_dwordx4 v[180:181], off nt
	v_lshl_add_u64 v[180:181], s[42:43], 0, v[134:135]
	s_mov_b32 m0, s18
	s_nop 0
	global_load_lds_dwordx4 v[180:181], off
	s_mov_b32 m0, s19
	s_nop 0
	global_load_lds_dwordx4 v[194:195], off
	s_waitcnt vmcnt(8)
	s_waitcnt lgkmcnt(0)
	s_barrier
	s_setprio 1
	s_waitcnt lgkmcnt(0)
	v_mfma_f32_16x16x32_bf16 v[60:63], v[140:143], v[182:185], v[60:63]
	v_mfma_f32_16x16x32_bf16 v[56:59], v[152:155], v[182:185], v[56:59]
	v_mfma_f32_16x16x32_bf16 v[52:55], v[140:143], v[190:193], v[52:55]
	v_mfma_f32_16x16x32_bf16 v[44:47], v[152:155], v[190:193], v[44:47]
	v_mfma_f32_16x16x32_bf16 v[36:39], v[140:143], v[218:221], v[36:39]
	v_mfma_f32_16x16x32_bf16 v[28:31], v[152:155], v[218:221], v[28:31]
	v_mfma_f32_16x16x32_bf16 v[20:23], v[140:143], v[226:229], v[20:23]
	v_mfma_f32_16x16x32_bf16 v[12:15], v[152:155], v[226:229], v[12:15]
	v_mfma_f32_16x16x32_bf16 v[60:63], v[148:151], v[186:189], v[60:63]
	v_mfma_f32_16x16x32_bf16 v[56:59], v[156:159], v[186:189], v[56:59]
	v_mfma_f32_16x16x32_bf16 v[52:55], v[148:151], v[214:217], v[52:55]
	v_mfma_f32_16x16x32_bf16 v[44:47], v[156:159], v[214:217], v[44:47]
	v_mfma_f32_16x16x32_bf16 v[36:39], v[148:151], v[222:225], v[36:39]
	v_mfma_f32_16x16x32_bf16 v[28:31], v[156:159], v[222:225], v[28:31]
	v_mfma_f32_16x16x32_bf16 v[20:23], v[148:151], v[230:233], v[20:23]
	v_mfma_f32_16x16x32_bf16 v[12:15], v[156:159], v[230:233], v[12:15]
	s_setprio 0
	s_setprio 1
	v_mfma_f32_16x16x32_bf16 v[48:51], v[160:163], v[182:185], v[48:51]
	v_mfma_f32_16x16x32_bf16 v[40:43], v[168:171], v[182:185], v[40:43]
	v_mfma_f32_16x16x32_bf16 v[32:35], v[160:163], v[190:193], v[32:35]
	v_mfma_f32_16x16x32_bf16 v[24:27], v[168:171], v[190:193], v[24:27]
	v_mfma_f32_16x16x32_bf16 v[16:19], v[160:163], v[218:221], v[16:19]
	v_mfma_f32_16x16x32_bf16 v[8:11], v[168:171], v[218:221], v[8:11]
	v_mfma_f32_16x16x32_bf16 v[4:7], v[160:163], v[226:229], v[4:7]
	v_mfma_f32_16x16x32_bf16 v[0:3], v[168:171], v[226:229], v[0:3]
	v_mfma_f32_16x16x32_bf16 v[48:51], v[164:167], v[186:189], v[48:51]
	v_mfma_f32_16x16x32_bf16 v[40:43], v[172:175], v[186:189], v[40:43]
	v_mfma_f32_16x16x32_bf16 v[32:35], v[164:167], v[214:217], v[32:35]
	v_mfma_f32_16x16x32_bf16 v[24:27], v[172:175], v[214:217], v[24:27]
	v_mfma_f32_16x16x32_bf16 v[16:19], v[164:167], v[222:225], v[16:19]
	v_mfma_f32_16x16x32_bf16 v[8:11], v[172:175], v[222:225], v[8:11]
	v_mfma_f32_16x16x32_bf16 v[4:7], v[164:167], v[230:233], v[4:7]
	v_mfma_f32_16x16x32_bf16 v[0:3], v[172:175], v[230:233], v[0:3]
	s_setprio 0
	s_barrier
	s_add_i32 s3, 0, 0x18000
	s_add_i32 s51, 0, 0x1c000
	v_add_u32_e32 v156, s3, v145
	v_add_u32_e32 v172, s51, v145
	ds_read_b128 v[140:143], v156
	ds_read_b128 v[148:151], v156 offset:1024
	ds_read_b128 v[152:155], v156 offset:2048
	ds_read_b128 v[156:159], v156 offset:3072
	ds_read_b128 v[160:163], v172
	ds_read_b128 v[164:167], v172 offset:1024
	ds_read_b128 v[168:171], v172 offset:2048
	ds_read_b128 v[172:175], v172 offset:3072
	s_add_u32 s6, s42, 0x80000
	s_addc_u32 s7, s43, 0
	s_mov_b32 m0, s20
	v_lshl_add_u64 v[202:203], s[6:7], 0, v[134:135]
	ds_read_b128 v[182:185], v147 offset:32768
	ds_read_b128 v[186:189], v147 offset:33792
	ds_read_b128 v[190:193], v147 offset:34816
	ds_read_b128 v[214:217], v147 offset:35840
	ds_read_b128 v[218:221], v147 offset:36864
	ds_read_b128 v[222:225], v147 offset:37888
	ds_read_b128 v[226:229], v147 offset:38912
	ds_read_b128 v[230:233], v147 offset:39936
	global_load_lds_dwordx4 v[202:203], off
	v_lshl_add_u64 v[202:203], s[6:7], 0, v[132:133]
	s_mov_b32 m0, s36
	s_nop 0
	global_load_lds_dwordx4 v[202:203], off
	s_waitcnt vmcnt(8)
	s_waitcnt lgkmcnt(0)
	s_barrier
	s_setprio 1
	s_waitcnt lgkmcnt(0)
	v_mfma_f32_16x16x32_bf16 v[126:129], v[140:143], v[182:185], v[126:129]
	v_mfma_f32_16x16x32_bf16 v[122:125], v[152:155], v[182:185], v[122:125]
	v_mfma_f32_16x16x32_bf16 v[118:121], v[140:143], v[190:193], v[118:121]
	v_mfma_f32_16x16x32_bf16 v[110:113], v[152:155], v[190:193], v[110:113]
	v_mfma_f32_16x16x32_bf16 v[102:105], v[140:143], v[218:221], v[102:105]
	v_mfma_f32_16x16x32_bf16 v[92:95], v[152:155], v[218:221], v[92:95]
	v_mfma_f32_16x16x32_bf16 v[84:87], v[140:143], v[226:229], v[84:87]
	v_mfma_f32_16x16x32_bf16 v[76:79], v[152:155], v[226:229], v[76:79]
	v_mfma_f32_16x16x32_bf16 v[126:129], v[148:151], v[186:189], v[126:129]
	v_mfma_f32_16x16x32_bf16 v[122:125], v[156:159], v[186:189], v[122:125]
	v_mfma_f32_16x16x32_bf16 v[118:121], v[148:151], v[214:217], v[118:121]
	v_mfma_f32_16x16x32_bf16 v[110:113], v[156:159], v[214:217], v[110:113]
	v_mfma_f32_16x16x32_bf16 v[102:105], v[148:151], v[222:225], v[102:105]
	v_mfma_f32_16x16x32_bf16 v[92:95], v[156:159], v[222:225], v[92:95]
	v_mfma_f32_16x16x32_bf16 v[84:87], v[148:151], v[230:233], v[84:87]
	v_mfma_f32_16x16x32_bf16 v[76:79], v[156:159], v[230:233], v[76:79]
	s_setprio 0
	s_setprio 1
	v_mfma_f32_16x16x32_bf16 v[114:117], v[160:163], v[182:185], v[114:117]
	v_mfma_f32_16x16x32_bf16 v[106:109], v[168:171], v[182:185], v[106:109]
	v_mfma_f32_16x16x32_bf16 v[98:101], v[160:163], v[190:193], v[98:101]
	v_mfma_f32_16x16x32_bf16 v[88:91], v[168:171], v[190:193], v[88:91]
	v_mfma_f32_16x16x32_bf16 v[80:83], v[160:163], v[218:221], v[80:83]
	v_mfma_f32_16x16x32_bf16 v[72:75], v[168:171], v[218:221], v[72:75]
	v_mfma_f32_16x16x32_bf16 v[68:71], v[160:163], v[226:229], v[68:71]
	v_mfma_f32_16x16x32_bf16 v[64:67], v[168:171], v[226:229], v[64:67]
	v_mfma_f32_16x16x32_bf16 v[114:117], v[164:167], v[186:189], v[114:117]
	v_mfma_f32_16x16x32_bf16 v[106:109], v[172:175], v[186:189], v[106:109]
	v_mfma_f32_16x16x32_bf16 v[98:101], v[164:167], v[214:217], v[98:101]
	v_mfma_f32_16x16x32_bf16 v[88:91], v[172:175], v[214:217], v[88:91]
	v_mfma_f32_16x16x32_bf16 v[80:83], v[164:167], v[222:225], v[80:83]
	v_mfma_f32_16x16x32_bf16 v[72:75], v[172:175], v[222:225], v[72:75]
	v_mfma_f32_16x16x32_bf16 v[68:71], v[164:167], v[230:233], v[68:71]
	v_mfma_f32_16x16x32_bf16 v[64:67], v[172:175], v[230:233], v[64:67]
	s_setprio 0
	s_barrier
	s_add_i32 s3, s3, s17
	v_lshl_add_u64 v[176:177], v[176:177], 0, s[30:31]
	s_mov_b32 m0, s3
	ds_read_b128 v[182:185], v147 offset:49152
	ds_read_b128 v[186:189], v147 offset:50176
	ds_read_b128 v[190:193], v147 offset:51200
	ds_read_b128 v[214:217], v147 offset:52224
	ds_read_b128 v[218:221], v147 offset:53248
	ds_read_b128 v[222:225], v147 offset:54272
	ds_read_b128 v[226:229], v147 offset:55296
	ds_read_b128 v[230:233], v147 offset:56320
	global_load_lds_dwordx4 v[176:177], off nt
	s_add_i32 m0, s3, 0x2000
	s_add_u32 s6, s38, 0x80080
	v_lshl_add_u64 v[176:177], v[178:179], 0, s[30:31]
	s_addc_u32 s7, s39, 0
	s_add_i32 s3, s51, s17
	global_load_lds_dwordx4 v[176:177], off nt
	v_lshl_add_u64 v[176:177], s[6:7], 0, v[96:97]
	s_mov_b32 m0, s3
	s_nop 0
	global_load_lds_dwordx4 v[176:177], off nt
	v_lshl_add_u64 v[176:177], s[6:7], 0, v[130:131]
	s_add_i32 m0, s3, 0x2000
	s_nop 0
	global_load_lds_dwordx4 v[176:177], off nt
	v_lshl_add_u64 v[176:177], v[180:181], 0, s[30:31]
	s_mov_b32 m0, s37
	s_nop 0
	global_load_lds_dwordx4 v[176:177], off
	v_lshl_add_u64 v[176:177], v[194:195], 0, s[30:31]
	s_mov_b32 m0, s40
	s_nop 0
	global_load_lds_dwordx4 v[176:177], off
	s_waitcnt vmcnt(8)
	s_waitcnt lgkmcnt(0)
	s_barrier
	s_setprio 1
	s_waitcnt lgkmcnt(0)
	v_mfma_f32_16x16x32_bf16 v[60:63], v[140:143], v[182:185], v[60:63]
	v_mfma_f32_16x16x32_bf16 v[56:59], v[152:155], v[182:185], v[56:59]
	v_mfma_f32_16x16x32_bf16 v[52:55], v[140:143], v[190:193], v[52:55]
	v_mfma_f32_16x16x32_bf16 v[44:47], v[152:155], v[190:193], v[44:47]
	v_mfma_f32_16x16x32_bf16 v[36:39], v[140:143], v[218:221], v[36:39]
	v_mfma_f32_16x16x32_bf16 v[28:31], v[152:155], v[218:221], v[28:31]
	v_mfma_f32_16x16x32_bf16 v[20:23], v[140:143], v[226:229], v[20:23]
	v_mfma_f32_16x16x32_bf16 v[12:15], v[152:155], v[226:229], v[12:15]
	v_mfma_f32_16x16x32_bf16 v[60:63], v[148:151], v[186:189], v[60:63]
	v_mfma_f32_16x16x32_bf16 v[56:59], v[156:159], v[186:189], v[56:59]
	v_mfma_f32_16x16x32_bf16 v[52:55], v[148:151], v[214:217], v[52:55]
	v_mfma_f32_16x16x32_bf16 v[44:47], v[156:159], v[214:217], v[44:47]
	v_mfma_f32_16x16x32_bf16 v[36:39], v[148:151], v[222:225], v[36:39]
	v_mfma_f32_16x16x32_bf16 v[28:31], v[156:159], v[222:225], v[28:31]
	v_mfma_f32_16x16x32_bf16 v[20:23], v[148:151], v[230:233], v[20:23]
	v_mfma_f32_16x16x32_bf16 v[12:15], v[156:159], v[230:233], v[12:15]
	s_setprio 0
	s_setprio 1
	v_mfma_f32_16x16x32_bf16 v[48:51], v[160:163], v[182:185], v[48:51]
	v_mfma_f32_16x16x32_bf16 v[40:43], v[168:171], v[182:185], v[40:43]
	v_mfma_f32_16x16x32_bf16 v[32:35], v[160:163], v[190:193], v[32:35]
	v_mfma_f32_16x16x32_bf16 v[24:27], v[168:171], v[190:193], v[24:27]
	v_mfma_f32_16x16x32_bf16 v[16:19], v[160:163], v[218:221], v[16:19]
	v_mfma_f32_16x16x32_bf16 v[8:11], v[168:171], v[218:221], v[8:11]
	v_mfma_f32_16x16x32_bf16 v[4:7], v[160:163], v[226:229], v[4:7]
	v_mfma_f32_16x16x32_bf16 v[0:3], v[168:171], v[226:229], v[0:3]
	v_mfma_f32_16x16x32_bf16 v[48:51], v[164:167], v[186:189], v[48:51]
	v_mfma_f32_16x16x32_bf16 v[40:43], v[172:175], v[186:189], v[40:43]
	v_mfma_f32_16x16x32_bf16 v[32:35], v[164:167], v[214:217], v[32:35]
	v_mfma_f32_16x16x32_bf16 v[24:27], v[172:175], v[214:217], v[24:27]
	v_mfma_f32_16x16x32_bf16 v[16:19], v[164:167], v[222:225], v[16:19]
	v_mfma_f32_16x16x32_bf16 v[8:11], v[172:175], v[222:225], v[8:11]
	v_mfma_f32_16x16x32_bf16 v[4:7], v[164:167], v[230:233], v[4:7]
	v_mfma_f32_16x16x32_bf16 v[0:3], v[172:175], v[230:233], v[0:3]
	s_setprio 0
	s_barrier
	s_add_i32 s2, s2, 2
	s_add_u32 s34, s34, 0x100
	s_addc_u32 s35, s35, 0
	s_add_u32 s49, s49, 0x100
	s_addc_u32 s50, s50, 0
	s_cmp_gt_u32 s2, 29
	s_cbranch_scc0 .LBB0_246
	s_and_b64 vcc, exec, s[10:11]
	s_cbranch_vccz .LBB0_249
	s_barrier

.LBB0_421:
	s_add_u32 s3, s22, 0xfffe0080
	s_addc_u32 s6, s23, -1
	s_add_i32 s7, 0, 0x10000
	s_cmp_eq_u32 s2, 4
	s_cselect_b32 s35, s4, s6
	s_cselect_b32 s34, s5, s3
	v_add_u32_e32 v96, s7, v176
	s_cselect_b32 s25, s9, s17
	s_cselect_b32 s24, s13, s15
	s_add_i32 s3, 0, 0x14000
	ds_read_b128 v[56:59], v96
	ds_read_b128 v[60:63], v96 offset:1024
	ds_read_b128 v[138:141], v96 offset:2048
	ds_read_b128 v[142:145], v96 offset:3072
	v_add_u32_e32 v96, s3, v176
	ds_read_b128 v[146:149], v96
	ds_read_b128 v[150:153], v96 offset:1024
	ds_read_b128 v[154:157], v96 offset:2048
	ds_read_b128 v[170:173], v96 offset:3072
	v_lshl_add_u64 v[174:175], s[22:23], 0, v[166:167]
	s_add_i32 m0, s75, 0xc000
	ds_read_b128 v[182:185], v177
	ds_read_b128 v[186:189], v177 offset:1024
	ds_read_b128 v[190:193], v177 offset:2048
	ds_read_b128 v[214:217], v177 offset:3072
	ds_read_b128 v[218:221], v177 offset:4096
	ds_read_b128 v[222:225], v177 offset:5120
	ds_read_b128 v[226:229], v177 offset:6144
	ds_read_b128 v[230:233], v177 offset:7168
	global_load_lds_dwordx4 v[174:175], off
	v_lshl_add_u64 v[174:175], s[22:23], 0, v[168:169]
	s_add_i32 m0, s75, 0xe000
	s_nop 0
	global_load_lds_dwordx4 v[174:175], off
	s_waitcnt vmcnt(8)
	s_waitcnt lgkmcnt(0)
	s_barrier
	s_setprio 1
	s_waitcnt lgkmcnt(0)
	v_mfma_f32_16x16x32_bf16 v[134:137], v[56:59], v[182:185], v[134:137]
	v_mfma_f32_16x16x32_bf16 v[130:133], v[138:141], v[182:185], v[130:133]
	v_mfma_f32_16x16x32_bf16 v[118:121], v[56:59], v[190:193], v[118:121]
	v_mfma_f32_16x16x32_bf16 v[114:117], v[138:141], v[190:193], v[114:117]
	v_mfma_f32_16x16x32_bf16 v[102:105], v[56:59], v[218:221], v[102:105]
	v_mfma_f32_16x16x32_bf16 v[98:101], v[138:141], v[218:221], v[98:101]
	v_mfma_f32_16x16x32_bf16 v[84:87], v[56:59], v[226:229], v[84:87]
	v_mfma_f32_16x16x32_bf16 v[80:83], v[138:141], v[226:229], v[80:83]
	v_mfma_f32_16x16x32_bf16 v[134:137], v[60:63], v[186:189], v[134:137]
	v_mfma_f32_16x16x32_bf16 v[130:133], v[142:145], v[186:189], v[130:133]
	v_mfma_f32_16x16x32_bf16 v[118:121], v[60:63], v[214:217], v[118:121]
	v_mfma_f32_16x16x32_bf16 v[114:117], v[142:145], v[214:217], v[114:117]
	v_mfma_f32_16x16x32_bf16 v[102:105], v[60:63], v[222:225], v[102:105]
	v_mfma_f32_16x16x32_bf16 v[98:101], v[142:145], v[222:225], v[98:101]
	v_mfma_f32_16x16x32_bf16 v[84:87], v[60:63], v[230:233], v[84:87]
	v_mfma_f32_16x16x32_bf16 v[80:83], v[142:145], v[230:233], v[80:83]
	s_setprio 0
	s_setprio 1
	v_mfma_f32_16x16x32_bf16 v[126:129], v[146:149], v[182:185], v[126:129]
	v_mfma_f32_16x16x32_bf16 v[122:125], v[154:157], v[182:185], v[122:125]
	v_mfma_f32_16x16x32_bf16 v[110:113], v[146:149], v[190:193], v[110:113]
	v_mfma_f32_16x16x32_bf16 v[106:109], v[154:157], v[190:193], v[106:109]
	v_mfma_f32_16x16x32_bf16 v[92:95], v[146:149], v[218:221], v[92:95]
	v_mfma_f32_16x16x32_bf16 v[88:91], v[154:157], v[218:221], v[88:91]
	v_mfma_f32_16x16x32_bf16 v[76:79], v[146:149], v[226:229], v[76:79]
	v_mfma_f32_16x16x32_bf16 v[72:75], v[154:157], v[226:229], v[72:75]
	v_mfma_f32_16x16x32_bf16 v[126:129], v[150:153], v[186:189], v[126:129]
	v_mfma_f32_16x16x32_bf16 v[122:125], v[170:173], v[186:189], v[122:125]
	v_mfma_f32_16x16x32_bf16 v[110:113], v[150:153], v[214:217], v[110:113]
	v_mfma_f32_16x16x32_bf16 v[106:109], v[170:173], v[214:217], v[106:109]
	v_mfma_f32_16x16x32_bf16 v[92:95], v[150:153], v[222:225], v[92:95]
	v_mfma_f32_16x16x32_bf16 v[88:91], v[170:173], v[222:225], v[88:91]
	v_mfma_f32_16x16x32_bf16 v[76:79], v[150:153], v[230:233], v[76:79]
	v_mfma_f32_16x16x32_bf16 v[72:75], v[170:173], v[230:233], v[72:75]
	s_setprio 0
	s_barrier
	s_add_i32 s6, s7, s74
	v_lshl_add_u64 v[174:175], s[24:25], 0, v[160:161]
	s_mov_b32 m0, s6
	ds_read_b128 v[182:185], v177 offset:16384
	ds_read_b128 v[186:189], v177 offset:17408
	ds_read_b128 v[190:193], v177 offset:18432
	ds_read_b128 v[214:217], v177 offset:19456
	ds_read_b128 v[218:221], v177 offset:20480
	ds_read_b128 v[222:225], v177 offset:21504
	ds_read_b128 v[226:229], v177 offset:22528
	ds_read_b128 v[230:233], v177 offset:23552
	global_load_lds_dwordx4 v[174:175], off nt
	s_add_i32 m0, s6, 0x2000
	s_add_u32 s6, s24, 0x20000
	v_lshl_add_u64 v[178:179], s[24:25], 0, v[164:165]
	s_addc_u32 s7, s25, 0
	s_add_i32 s3, s3, s74
	global_load_lds_dwordx4 v[178:179], off nt
	v_lshl_add_u64 v[180:181], s[6:7], 0, v[160:161]
	s_mov_b32 m0, s3
	v_lshl_add_u64 v[194:195], s[34:35], 0, v[162:163]
	global_load_lds_dwordx4 v[180:181], off nt
	v_lshl_add_u64 v[180:181], s[6:7], 0, v[164:165]
	s_add_i32 m0, s3, 0x2000
	s_nop 0
	global_load_lds_dwordx4 v[180:181], off nt
	v_lshl_add_u64 v[180:181], s[34:35], 0, v[158:159]
	s_mov_b32 m0, s75
	s_nop 0
	global_load_lds_dwordx4 v[180:181], off
	s_mov_b32 m0, s82
	s_nop 0
	global_load_lds_dwordx4 v[194:195], off
	s_waitcnt vmcnt(8)
	s_waitcnt lgkmcnt(0)
	s_barrier
	s_setprio 1
	s_waitcnt lgkmcnt(0)
	v_mfma_f32_16x16x32_bf16 v[68:71], v[56:59], v[182:185], v[68:71]
	v_mfma_f32_16x16x32_bf16 v[64:67], v[138:141], v[182:185], v[64:67]
	v_mfma_f32_16x16x32_bf16 v[44:47], v[56:59], v[190:193], v[44:47]
	v_mfma_f32_16x16x32_bf16 v[40:43], v[138:141], v[190:193], v[40:43]
	v_mfma_f32_16x16x32_bf16 v[28:31], v[56:59], v[218:221], v[28:31]
	v_mfma_f32_16x16x32_bf16 v[24:27], v[138:141], v[218:221], v[24:27]
	v_mfma_f32_16x16x32_bf16 v[12:15], v[56:59], v[226:229], v[12:15]
	v_mfma_f32_16x16x32_bf16 v[8:11], v[138:141], v[226:229], v[8:11]
	v_mfma_f32_16x16x32_bf16 v[68:71], v[60:63], v[186:189], v[68:71]
	v_mfma_f32_16x16x32_bf16 v[64:67], v[142:145], v[186:189], v[64:67]
	v_mfma_f32_16x16x32_bf16 v[44:47], v[60:63], v[214:217], v[44:47]
	v_mfma_f32_16x16x32_bf16 v[40:43], v[142:145], v[214:217], v[40:43]
	v_mfma_f32_16x16x32_bf16 v[28:31], v[60:63], v[222:225], v[28:31]
	v_mfma_f32_16x16x32_bf16 v[24:27], v[142:145], v[222:225], v[24:27]
	v_mfma_f32_16x16x32_bf16 v[12:15], v[60:63], v[230:233], v[12:15]
	v_mfma_f32_16x16x32_bf16 v[8:11], v[142:145], v[230:233], v[8:11]
	s_setprio 0
	s_setprio 1
	v_mfma_f32_16x16x32_bf16 v[52:55], v[146:149], v[182:185], v[52:55]
	v_mfma_f32_16x16x32_bf16 v[48:51], v[154:157], v[182:185], v[48:51]
	v_mfma_f32_16x16x32_bf16 v[36:39], v[146:149], v[190:193], v[36:39]
	v_mfma_f32_16x16x32_bf16 v[32:35], v[154:157], v[190:193], v[32:35]
	v_mfma_f32_16x16x32_bf16 v[20:23], v[146:149], v[218:221], v[20:23]
	v_mfma_f32_16x16x32_bf16 v[16:19], v[154:157], v[218:221], v[16:19]
	v_mfma_f32_16x16x32_bf16 v[4:7], v[146:149], v[226:229], v[4:7]
	v_mfma_f32_16x16x32_bf16 v[0:3], v[154:157], v[226:229], v[0:3]
	v_mfma_f32_16x16x32_bf16 v[52:55], v[150:153], v[186:189], v[52:55]
	v_mfma_f32_16x16x32_bf16 v[48:51], v[170:173], v[186:189], v[48:51]
	v_mfma_f32_16x16x32_bf16 v[36:39], v[150:153], v[214:217], v[36:39]
	v_mfma_f32_16x16x32_bf16 v[32:35], v[170:173], v[214:217], v[32:35]
	v_mfma_f32_16x16x32_bf16 v[20:23], v[150:153], v[222:225], v[20:23]
	v_mfma_f32_16x16x32_bf16 v[16:19], v[170:173], v[222:225], v[16:19]
	v_mfma_f32_16x16x32_bf16 v[4:7], v[150:153], v[230:233], v[4:7]
	v_mfma_f32_16x16x32_bf16 v[0:3], v[170:173], v[230:233], v[0:3]
	s_setprio 0
	s_barrier
	s_add_i32 s3, 0, 0x18000
	v_add_u32_e32 v96, s3, v176
	s_add_i32 s18, 0, 0x1c000
	ds_read_b128 v[56:59], v96
	ds_read_b128 v[60:63], v96 offset:1024
	ds_read_b128 v[138:141], v96 offset:2048
	ds_read_b128 v[142:145], v96 offset:3072
	v_add_u32_e32 v96, s18, v176
	ds_read_b128 v[146:149], v96
	ds_read_b128 v[150:153], v96 offset:1024
	ds_read_b128 v[154:157], v96 offset:2048
	ds_read_b128 v[170:173], v96 offset:3072
	s_add_u32 s6, s34, 0x20000
	s_addc_u32 s7, s35, 0
	s_mov_b32 m0, s83
	v_lshl_add_u64 v[202:203], s[6:7], 0, v[158:159]
	ds_read_b128 v[182:185], v177 offset:32768
	ds_read_b128 v[186:189], v177 offset:33792
	ds_read_b128 v[190:193], v177 offset:34816
	ds_read_b128 v[214:217], v177 offset:35840
	ds_read_b128 v[218:221], v177 offset:36864
	ds_read_b128 v[222:225], v177 offset:37888
	ds_read_b128 v[226:229], v177 offset:38912
	ds_read_b128 v[230:233], v177 offset:39936
	global_load_lds_dwordx4 v[202:203], off
	v_lshl_add_u64 v[202:203], s[6:7], 0, v[162:163]
	s_mov_b32 m0, s88
	s_nop 0
	global_load_lds_dwordx4 v[202:203], off
	s_waitcnt vmcnt(8)
	s_waitcnt lgkmcnt(0)
	s_barrier
	s_setprio 1
	s_waitcnt lgkmcnt(0)
	v_mfma_f32_16x16x32_bf16 v[134:137], v[56:59], v[182:185], v[134:137]
	v_mfma_f32_16x16x32_bf16 v[130:133], v[138:141], v[182:185], v[130:133]
	v_mfma_f32_16x16x32_bf16 v[118:121], v[56:59], v[190:193], v[118:121]
	v_mfma_f32_16x16x32_bf16 v[114:117], v[138:141], v[190:193], v[114:117]
	v_mfma_f32_16x16x32_bf16 v[102:105], v[56:59], v[218:221], v[102:105]
	v_mfma_f32_16x16x32_bf16 v[98:101], v[138:141], v[218:221], v[98:101]
	v_mfma_f32_16x16x32_bf16 v[84:87], v[56:59], v[226:229], v[84:87]
	v_mfma_f32_16x16x32_bf16 v[80:83], v[138:141], v[226:229], v[80:83]
	v_mfma_f32_16x16x32_bf16 v[134:137], v[60:63], v[186:189], v[134:137]
	v_mfma_f32_16x16x32_bf16 v[130:133], v[142:145], v[186:189], v[130:133]
	v_mfma_f32_16x16x32_bf16 v[118:121], v[60:63], v[214:217], v[118:121]
	v_mfma_f32_16x16x32_bf16 v[114:117], v[142:145], v[214:217], v[114:117]
	v_mfma_f32_16x16x32_bf16 v[102:105], v[60:63], v[222:225], v[102:105]
	v_mfma_f32_16x16x32_bf16 v[98:101], v[142:145], v[222:225], v[98:101]
	v_mfma_f32_16x16x32_bf16 v[84:87], v[60:63], v[230:233], v[84:87]
	v_mfma_f32_16x16x32_bf16 v[80:83], v[142:145], v[230:233], v[80:83]
	s_setprio 0
	s_setprio 1
	v_mfma_f32_16x16x32_bf16 v[126:129], v[146:149], v[182:185], v[126:129]
	v_mfma_f32_16x16x32_bf16 v[122:125], v[154:157], v[182:185], v[122:125]
	v_mfma_f32_16x16x32_bf16 v[110:113], v[146:149], v[190:193], v[110:113]
	v_mfma_f32_16x16x32_bf16 v[106:109], v[154:157], v[190:193], v[106:109]
	v_mfma_f32_16x16x32_bf16 v[92:95], v[146:149], v[218:221], v[92:95]
	v_mfma_f32_16x16x32_bf16 v[88:91], v[154:157], v[218:221], v[88:91]
	v_mfma_f32_16x16x32_bf16 v[76:79], v[146:149], v[226:229], v[76:79]
	v_mfma_f32_16x16x32_bf16 v[72:75], v[154:157], v[226:229], v[72:75]
	v_mfma_f32_16x16x32_bf16 v[126:129], v[150:153], v[186:189], v[126:129]
	v_mfma_f32_16x16x32_bf16 v[122:125], v[170:173], v[186:189], v[122:125]
	v_mfma_f32_16x16x32_bf16 v[110:113], v[150:153], v[214:217], v[110:113]
	v_mfma_f32_16x16x32_bf16 v[106:109], v[170:173], v[214:217], v[106:109]
	v_mfma_f32_16x16x32_bf16 v[92:95], v[150:153], v[222:225], v[92:95]
	v_mfma_f32_16x16x32_bf16 v[88:91], v[170:173], v[222:225], v[88:91]
	v_mfma_f32_16x16x32_bf16 v[76:79], v[150:153], v[230:233], v[76:79]
	v_mfma_f32_16x16x32_bf16 v[72:75], v[170:173], v[230:233], v[72:75]
	s_setprio 0
	s_barrier
	s_add_i32 s3, s3, s74
	v_lshl_add_u64 v[174:175], v[174:175], 0, s[30:31]
	s_mov_b32 m0, s3
	ds_read_b128 v[182:185], v177 offset:49152
	ds_read_b128 v[186:189], v177 offset:50176
	ds_read_b128 v[190:193], v177 offset:51200
	ds_read_b128 v[214:217], v177 offset:52224
	ds_read_b128 v[218:221], v177 offset:53248
	ds_read_b128 v[222:225], v177 offset:54272
	ds_read_b128 v[226:229], v177 offset:55296
	ds_read_b128 v[230:233], v177 offset:56320
	global_load_lds_dwordx4 v[174:175], off nt
	s_add_i32 m0, s3, 0x2000
	s_add_u32 s6, s24, 0x20080
	v_lshl_add_u64 v[174:175], v[178:179], 0, s[30:31]
	s_addc_u32 s7, s25, 0
	s_add_i32 s3, s18, s74
	global_load_lds_dwordx4 v[174:175], off nt
	v_lshl_add_u64 v[174:175], s[6:7], 0, v[160:161]
	s_mov_b32 m0, s3
	s_nop 0
	global_load_lds_dwordx4 v[174:175], off nt
	v_lshl_add_u64 v[174:175], s[6:7], 0, v[164:165]
	s_add_i32 m0, s3, 0x2000
	s_nop 0
	global_load_lds_dwordx4 v[174:175], off nt
	v_lshl_add_u64 v[174:175], v[180:181], 0, s[30:31]
	s_mov_b32 m0, s97
	s_nop 0
	global_load_lds_dwordx4 v[174:175], off
	v_lshl_add_u64 v[174:175], v[194:195], 0, s[30:31]
	s_mov_b32 m0, s50
	s_nop 0
	global_load_lds_dwordx4 v[174:175], off
	s_waitcnt vmcnt(8)
	s_waitcnt lgkmcnt(0)
	s_barrier
	s_setprio 1
	s_waitcnt lgkmcnt(0)
	v_mfma_f32_16x16x32_bf16 v[68:71], v[56:59], v[182:185], v[68:71]
	v_mfma_f32_16x16x32_bf16 v[64:67], v[138:141], v[182:185], v[64:67]
	v_mfma_f32_16x16x32_bf16 v[44:47], v[56:59], v[190:193], v[44:47]
	v_mfma_f32_16x16x32_bf16 v[40:43], v[138:141], v[190:193], v[40:43]
	v_mfma_f32_16x16x32_bf16 v[28:31], v[56:59], v[218:221], v[28:31]
	v_mfma_f32_16x16x32_bf16 v[24:27], v[138:141], v[218:221], v[24:27]
	v_mfma_f32_16x16x32_bf16 v[12:15], v[56:59], v[226:229], v[12:15]
	v_mfma_f32_16x16x32_bf16 v[8:11], v[138:141], v[226:229], v[8:11]
	v_mfma_f32_16x16x32_bf16 v[68:71], v[60:63], v[186:189], v[68:71]
	v_mfma_f32_16x16x32_bf16 v[64:67], v[142:145], v[186:189], v[64:67]
	v_mfma_f32_16x16x32_bf16 v[44:47], v[60:63], v[214:217], v[44:47]
	v_mfma_f32_16x16x32_bf16 v[40:43], v[142:145], v[214:217], v[40:43]
	v_mfma_f32_16x16x32_bf16 v[28:31], v[60:63], v[222:225], v[28:31]
	v_mfma_f32_16x16x32_bf16 v[24:27], v[142:145], v[222:225], v[24:27]
	v_mfma_f32_16x16x32_bf16 v[12:15], v[60:63], v[230:233], v[12:15]
	v_mfma_f32_16x16x32_bf16 v[8:11], v[142:145], v[230:233], v[8:11]
	s_setprio 0
	s_setprio 1
	v_mfma_f32_16x16x32_bf16 v[52:55], v[146:149], v[182:185], v[52:55]
	v_mfma_f32_16x16x32_bf16 v[48:51], v[154:157], v[182:185], v[48:51]
	v_mfma_f32_16x16x32_bf16 v[36:39], v[146:149], v[190:193], v[36:39]
	v_mfma_f32_16x16x32_bf16 v[32:35], v[154:157], v[190:193], v[32:35]
	v_mfma_f32_16x16x32_bf16 v[20:23], v[146:149], v[218:221], v[20:23]
	v_mfma_f32_16x16x32_bf16 v[16:19], v[154:157], v[218:221], v[16:19]
	v_mfma_f32_16x16x32_bf16 v[4:7], v[146:149], v[226:229], v[4:7]
	v_mfma_f32_16x16x32_bf16 v[0:3], v[154:157], v[226:229], v[0:3]
	v_mfma_f32_16x16x32_bf16 v[52:55], v[150:153], v[186:189], v[52:55]
	v_mfma_f32_16x16x32_bf16 v[48:51], v[170:173], v[186:189], v[48:51]
	v_mfma_f32_16x16x32_bf16 v[36:39], v[150:153], v[214:217], v[36:39]
	v_mfma_f32_16x16x32_bf16 v[32:35], v[170:173], v[214:217], v[32:35]
	v_mfma_f32_16x16x32_bf16 v[20:23], v[150:153], v[222:225], v[20:23]
	v_mfma_f32_16x16x32_bf16 v[16:19], v[170:173], v[222:225], v[16:19]
	v_mfma_f32_16x16x32_bf16 v[4:7], v[150:153], v[230:233], v[4:7]
	v_mfma_f32_16x16x32_bf16 v[0:3], v[170:173], v[230:233], v[0:3]
	s_setprio 0
	s_barrier
	s_add_i32 s2, s2, 2
	s_add_u32 s22, s22, 0x100
	s_addc_u32 s23, s23, 0
	s_add_u32 s15, s15, 0x100
	s_addc_u32 s17, s17, 0
	s_cmp_gt_u32 s2, 5
	s_cbranch_scc0 .LBB0_421
	s_and_b64 vcc, exec, s[58:59]
	s_cbranch_vccz .LBB0_424
	s_barrier

.LBB0_717:
	s_add_u32 s3, s42, 0xfffe0080
	s_addc_u32 s6, s43, -1
	s_add_i32 s7, 0, 0x10000
	s_cmp_eq_u32 s2, 4
	s_cselect_b32 s47, s23, s6
	s_cselect_b32 s46, s51, s3
	v_add_u32_e32 v140, s7, v143
	s_cselect_b32 s45, s15, s54
	s_cselect_b32 s44, s52, s53
	s_add_i32 s3, 0, 0x14000
	ds_read_b128 v[146:149], v140
	ds_read_b128 v[150:153], v140 offset:1024
	ds_read_b128 v[154:157], v140 offset:2048
	ds_read_b128 v[158:161], v140 offset:3072
	v_add_u32_e32 v140, s3, v143
	ds_read_b128 v[162:165], v140
	ds_read_b128 v[166:169], v140 offset:1024
	ds_read_b128 v[170:173], v140 offset:2048
	ds_read_b128 v[174:177], v140 offset:3072
	v_lshl_add_u64 v[140:141], s[42:43], 0, v[136:137]
	s_add_i32 m0, s20, 0xc000
	ds_read_b128 v[178:181], v145
	ds_read_b128 v[182:185], v145 offset:1024
	ds_read_b128 v[186:189], v145 offset:2048
	ds_read_b128 v[190:193], v145 offset:3072
	ds_read_b128 v[202:205], v145 offset:4096
	ds_read_b128 v[206:209], v145 offset:5120
	ds_read_b128 v[214:217], v145 offset:6144
	ds_read_b128 v[218:221], v145 offset:7168
	global_load_lds_dwordx4 v[140:141], off
	v_lshl_add_u64 v[140:141], s[42:43], 0, v[138:139]
	s_add_i32 m0, s20, 0xe000
	s_nop 0
	global_load_lds_dwordx4 v[140:141], off
	s_waitcnt vmcnt(8)
	s_waitcnt lgkmcnt(0)
	s_barrier
	s_setprio 1
	s_waitcnt lgkmcnt(0)
	v_mfma_f32_16x16x32_bf16 v[126:129], v[146:149], v[178:181], v[126:129]
	v_mfma_f32_16x16x32_bf16 v[122:125], v[154:157], v[178:181], v[122:125]
	v_mfma_f32_16x16x32_bf16 v[118:121], v[146:149], v[186:189], v[118:121]
	v_mfma_f32_16x16x32_bf16 v[110:113], v[154:157], v[186:189], v[110:113]
	v_mfma_f32_16x16x32_bf16 v[102:105], v[146:149], v[202:205], v[102:105]
	v_mfma_f32_16x16x32_bf16 v[92:95], v[154:157], v[202:205], v[92:95]
	v_mfma_f32_16x16x32_bf16 v[84:87], v[146:149], v[214:217], v[84:87]
	v_mfma_f32_16x16x32_bf16 v[76:79], v[154:157], v[214:217], v[76:79]
	v_mfma_f32_16x16x32_bf16 v[126:129], v[150:153], v[182:185], v[126:129]
	v_mfma_f32_16x16x32_bf16 v[122:125], v[158:161], v[182:185], v[122:125]
	v_mfma_f32_16x16x32_bf16 v[118:121], v[150:153], v[190:193], v[118:121]
	v_mfma_f32_16x16x32_bf16 v[110:113], v[158:161], v[190:193], v[110:113]
	v_mfma_f32_16x16x32_bf16 v[102:105], v[150:153], v[206:209], v[102:105]
	v_mfma_f32_16x16x32_bf16 v[92:95], v[158:161], v[206:209], v[92:95]
	v_mfma_f32_16x16x32_bf16 v[84:87], v[150:153], v[218:221], v[84:87]
	v_mfma_f32_16x16x32_bf16 v[76:79], v[158:161], v[218:221], v[76:79]
	s_setprio 0
	s_setprio 1
	v_mfma_f32_16x16x32_bf16 v[114:117], v[162:165], v[178:181], v[114:117]
	v_mfma_f32_16x16x32_bf16 v[106:109], v[170:173], v[178:181], v[106:109]
	v_mfma_f32_16x16x32_bf16 v[98:101], v[162:165], v[186:189], v[98:101]
	v_mfma_f32_16x16x32_bf16 v[88:91], v[170:173], v[186:189], v[88:91]
	v_mfma_f32_16x16x32_bf16 v[80:83], v[162:165], v[202:205], v[80:83]
	v_mfma_f32_16x16x32_bf16 v[72:75], v[170:173], v[202:205], v[72:75]
	v_mfma_f32_16x16x32_bf16 v[68:71], v[162:165], v[214:217], v[68:71]
	v_mfma_f32_16x16x32_bf16 v[64:67], v[170:173], v[214:217], v[64:67]
	v_mfma_f32_16x16x32_bf16 v[114:117], v[166:169], v[182:185], v[114:117]
	v_mfma_f32_16x16x32_bf16 v[106:109], v[174:177], v[182:185], v[106:109]
	v_mfma_f32_16x16x32_bf16 v[98:101], v[166:169], v[190:193], v[98:101]
	v_mfma_f32_16x16x32_bf16 v[88:91], v[174:177], v[190:193], v[88:91]
	v_mfma_f32_16x16x32_bf16 v[80:83], v[166:169], v[206:209], v[80:83]
	v_mfma_f32_16x16x32_bf16 v[72:75], v[174:177], v[206:209], v[72:75]
	v_mfma_f32_16x16x32_bf16 v[68:71], v[166:169], v[218:221], v[68:71]
	v_mfma_f32_16x16x32_bf16 v[64:67], v[174:177], v[218:221], v[64:67]
	s_setprio 0
	s_barrier
	s_add_i32 s6, s7, s4
	v_lshl_add_u64 v[140:141], s[44:45], 0, v[96:97]
	s_mov_b32 m0, s6
	ds_read_b128 v[178:181], v145 offset:16384
	ds_read_b128 v[182:185], v145 offset:17408
	ds_read_b128 v[186:189], v145 offset:18432
	ds_read_b128 v[190:193], v145 offset:19456
	ds_read_b128 v[202:205], v145 offset:20480
	ds_read_b128 v[206:209], v145 offset:21504
	ds_read_b128 v[214:217], v145 offset:22528
	ds_read_b128 v[218:221], v145 offset:23552
	global_load_lds_dwordx4 v[140:141], off nt
	s_add_i32 m0, s6, 0x2000
	s_add_u32 s6, s44, 0x20000
	v_lshl_add_u64 v[194:195], s[44:45], 0, v[134:135]
	s_addc_u32 s7, s45, 0
	s_add_i32 s3, s3, s4
	global_load_lds_dwordx4 v[194:195], off nt
	v_lshl_add_u64 v[198:199], s[6:7], 0, v[96:97]
	s_mov_b32 m0, s3
	v_lshl_add_u64 v[200:201], s[46:47], 0, v[132:133]
	global_load_lds_dwordx4 v[198:199], off nt
	v_lshl_add_u64 v[198:199], s[6:7], 0, v[134:135]
	s_add_i32 m0, s3, 0x2000
	s_nop 0
	global_load_lds_dwordx4 v[198:199], off nt
	v_lshl_add_u64 v[198:199], s[46:47], 0, v[130:131]
	s_mov_b32 m0, s20
	s_nop 0
	global_load_lds_dwordx4 v[198:199], off
	s_mov_b32 m0, s25
	s_nop 0
	global_load_lds_dwordx4 v[200:201], off
	s_waitcnt vmcnt(8)
	s_waitcnt lgkmcnt(0)
	s_barrier
	s_setprio 1
	s_waitcnt lgkmcnt(0)
	v_mfma_f32_16x16x32_bf16 v[60:63], v[146:149], v[178:181], v[60:63]
	v_mfma_f32_16x16x32_bf16 v[56:59], v[154:157], v[178:181], v[56:59]
	v_mfma_f32_16x16x32_bf16 v[52:55], v[146:149], v[186:189], v[52:55]
	v_mfma_f32_16x16x32_bf16 v[44:47], v[154:157], v[186:189], v[44:47]
	v_mfma_f32_16x16x32_bf16 v[36:39], v[146:149], v[202:205], v[36:39]
	v_mfma_f32_16x16x32_bf16 v[28:31], v[154:157], v[202:205], v[28:31]
	v_mfma_f32_16x16x32_bf16 v[20:23], v[146:149], v[214:217], v[20:23]
	v_mfma_f32_16x16x32_bf16 v[12:15], v[154:157], v[214:217], v[12:15]
	v_mfma_f32_16x16x32_bf16 v[60:63], v[150:153], v[182:185], v[60:63]
	v_mfma_f32_16x16x32_bf16 v[56:59], v[158:161], v[182:185], v[56:59]
	v_mfma_f32_16x16x32_bf16 v[52:55], v[150:153], v[190:193], v[52:55]
	v_mfma_f32_16x16x32_bf16 v[44:47], v[158:161], v[190:193], v[44:47]
	v_mfma_f32_16x16x32_bf16 v[36:39], v[150:153], v[206:209], v[36:39]
	v_mfma_f32_16x16x32_bf16 v[28:31], v[158:161], v[206:209], v[28:31]
	v_mfma_f32_16x16x32_bf16 v[20:23], v[150:153], v[218:221], v[20:23]
	v_mfma_f32_16x16x32_bf16 v[12:15], v[158:161], v[218:221], v[12:15]
	s_setprio 0
	s_setprio 1
	v_mfma_f32_16x16x32_bf16 v[48:51], v[162:165], v[178:181], v[48:51]
	v_mfma_f32_16x16x32_bf16 v[40:43], v[170:173], v[178:181], v[40:43]
	v_mfma_f32_16x16x32_bf16 v[32:35], v[162:165], v[186:189], v[32:35]
	v_mfma_f32_16x16x32_bf16 v[24:27], v[170:173], v[186:189], v[24:27]
	v_mfma_f32_16x16x32_bf16 v[16:19], v[162:165], v[202:205], v[16:19]
	v_mfma_f32_16x16x32_bf16 v[8:11], v[170:173], v[202:205], v[8:11]
	v_mfma_f32_16x16x32_bf16 v[4:7], v[162:165], v[214:217], v[4:7]
	v_mfma_f32_16x16x32_bf16 v[0:3], v[170:173], v[214:217], v[0:3]
	v_mfma_f32_16x16x32_bf16 v[48:51], v[166:169], v[182:185], v[48:51]
	v_mfma_f32_16x16x32_bf16 v[40:43], v[174:177], v[182:185], v[40:43]
	v_mfma_f32_16x16x32_bf16 v[32:35], v[166:169], v[190:193], v[32:35]
	v_mfma_f32_16x16x32_bf16 v[24:27], v[174:177], v[190:193], v[24:27]
	v_mfma_f32_16x16x32_bf16 v[16:19], v[166:169], v[206:209], v[16:19]
	v_mfma_f32_16x16x32_bf16 v[8:11], v[174:177], v[206:209], v[8:11]
	v_mfma_f32_16x16x32_bf16 v[4:7], v[166:169], v[218:221], v[4:7]
	v_mfma_f32_16x16x32_bf16 v[0:3], v[174:177], v[218:221], v[0:3]
	s_setprio 0
	s_barrier
	s_add_i32 s3, 0, 0x18000
	s_add_i32 s55, 0, 0x1c000
	v_add_u32_e32 v158, s3, v143
	v_add_u32_e32 v174, s55, v143
	ds_read_b128 v[146:149], v158
	ds_read_b128 v[150:153], v158 offset:1024
	ds_read_b128 v[154:157], v158 offset:2048
	ds_read_b128 v[158:161], v158 offset:3072
	ds_read_b128 v[162:165], v174
	ds_read_b128 v[166:169], v174 offset:1024
	ds_read_b128 v[170:173], v174 offset:2048
	ds_read_b128 v[174:177], v174 offset:3072
	s_add_u32 s6, s46, 0x20000
	s_addc_u32 s7, s47, 0
	s_mov_b32 m0, s36
	v_lshl_add_u64 v[222:223], s[6:7], 0, v[130:131]
	ds_read_b128 v[178:181], v145 offset:32768
	ds_read_b128 v[182:185], v145 offset:33792
	ds_read_b128 v[186:189], v145 offset:34816
	ds_read_b128 v[190:193], v145 offset:35840
	ds_read_b128 v[202:205], v145 offset:36864
	ds_read_b128 v[206:209], v145 offset:37888
	ds_read_b128 v[214:217], v145 offset:38912
	ds_read_b128 v[218:221], v145 offset:39936
	global_load_lds_dwordx4 v[222:223], off
	v_lshl_add_u64 v[222:223], s[6:7], 0, v[132:133]
	s_mov_b32 m0, s37
	s_nop 0
	global_load_lds_dwordx4 v[222:223], off
	s_waitcnt vmcnt(8)
	s_waitcnt lgkmcnt(0)
	s_barrier
	s_setprio 1
	s_waitcnt lgkmcnt(0)
	v_mfma_f32_16x16x32_bf16 v[126:129], v[146:149], v[178:181], v[126:129]
	v_mfma_f32_16x16x32_bf16 v[122:125], v[154:157], v[178:181], v[122:125]
	v_mfma_f32_16x16x32_bf16 v[118:121], v[146:149], v[186:189], v[118:121]
	v_mfma_f32_16x16x32_bf16 v[110:113], v[154:157], v[186:189], v[110:113]
	v_mfma_f32_16x16x32_bf16 v[102:105], v[146:149], v[202:205], v[102:105]
	v_mfma_f32_16x16x32_bf16 v[92:95], v[154:157], v[202:205], v[92:95]
	v_mfma_f32_16x16x32_bf16 v[84:87], v[146:149], v[214:217], v[84:87]
	v_mfma_f32_16x16x32_bf16 v[76:79], v[154:157], v[214:217], v[76:79]
	v_mfma_f32_16x16x32_bf16 v[126:129], v[150:153], v[182:185], v[126:129]
	v_mfma_f32_16x16x32_bf16 v[122:125], v[158:161], v[182:185], v[122:125]
	v_mfma_f32_16x16x32_bf16 v[118:121], v[150:153], v[190:193], v[118:121]
	v_mfma_f32_16x16x32_bf16 v[110:113], v[158:161], v[190:193], v[110:113]
	v_mfma_f32_16x16x32_bf16 v[102:105], v[150:153], v[206:209], v[102:105]
	v_mfma_f32_16x16x32_bf16 v[92:95], v[158:161], v[206:209], v[92:95]
	v_mfma_f32_16x16x32_bf16 v[84:87], v[150:153], v[218:221], v[84:87]
	v_mfma_f32_16x16x32_bf16 v[76:79], v[158:161], v[218:221], v[76:79]
	s_setprio 0
	s_setprio 1
	v_mfma_f32_16x16x32_bf16 v[114:117], v[162:165], v[178:181], v[114:117]
	v_mfma_f32_16x16x32_bf16 v[106:109], v[170:173], v[178:181], v[106:109]
	v_mfma_f32_16x16x32_bf16 v[98:101], v[162:165], v[186:189], v[98:101]
	v_mfma_f32_16x16x32_bf16 v[88:91], v[170:173], v[186:189], v[88:91]
	v_mfma_f32_16x16x32_bf16 v[80:83], v[162:165], v[202:205], v[80:83]
	v_mfma_f32_16x16x32_bf16 v[72:75], v[170:173], v[202:205], v[72:75]
	v_mfma_f32_16x16x32_bf16 v[68:71], v[162:165], v[214:217], v[68:71]
	v_mfma_f32_16x16x32_bf16 v[64:67], v[170:173], v[214:217], v[64:67]
	v_mfma_f32_16x16x32_bf16 v[114:117], v[166:169], v[182:185], v[114:117]
	v_mfma_f32_16x16x32_bf16 v[106:109], v[174:177], v[182:185], v[106:109]
	v_mfma_f32_16x16x32_bf16 v[98:101], v[166:169], v[190:193], v[98:101]
	v_mfma_f32_16x16x32_bf16 v[88:91], v[174:177], v[190:193], v[88:91]
	v_mfma_f32_16x16x32_bf16 v[80:83], v[166:169], v[206:209], v[80:83]
	v_mfma_f32_16x16x32_bf16 v[72:75], v[174:177], v[206:209], v[72:75]
	v_mfma_f32_16x16x32_bf16 v[68:71], v[166:169], v[218:221], v[68:71]
	v_mfma_f32_16x16x32_bf16 v[64:67], v[174:177], v[218:221], v[64:67]
	s_setprio 0
	s_barrier
	s_add_i32 s3, s3, s4
	v_lshl_add_u64 v[140:141], v[140:141], 0, s[30:31]
	s_mov_b32 m0, s3
	ds_read_b128 v[178:181], v145 offset:49152
	ds_read_b128 v[182:185], v145 offset:50176
	ds_read_b128 v[186:189], v145 offset:51200
	ds_read_b128 v[190:193], v145 offset:52224
	ds_read_b128 v[202:205], v145 offset:53248
	ds_read_b128 v[206:209], v145 offset:54272
	ds_read_b128 v[214:217], v145 offset:55296
	ds_read_b128 v[218:221], v145 offset:56320
	global_load_lds_dwordx4 v[140:141], off nt
	s_add_i32 m0, s3, 0x2000
	s_add_u32 s6, s44, 0x20080
	v_lshl_add_u64 v[140:141], v[194:195], 0, s[30:31]
	s_addc_u32 s7, s45, 0
	s_add_i32 s3, s55, s4
	global_load_lds_dwordx4 v[140:141], off nt
	v_lshl_add_u64 v[140:141], s[6:7], 0, v[96:97]
	s_mov_b32 m0, s3
	s_nop 0
	global_load_lds_dwordx4 v[140:141], off nt
	v_lshl_add_u64 v[140:141], s[6:7], 0, v[134:135]
	s_add_i32 m0, s3, 0x2000
	s_nop 0
	global_load_lds_dwordx4 v[140:141], off nt
	v_lshl_add_u64 v[140:141], v[198:199], 0, s[30:31]
	s_mov_b32 m0, s40
	s_nop 0
	global_load_lds_dwordx4 v[140:141], off
	v_lshl_add_u64 v[140:141], v[200:201], 0, s[30:31]
	s_mov_b32 m0, s48
	s_nop 0
	global_load_lds_dwordx4 v[140:141], off
	s_waitcnt vmcnt(8)
	s_waitcnt lgkmcnt(0)
	s_barrier
	s_setprio 1
	s_waitcnt lgkmcnt(0)
	v_mfma_f32_16x16x32_bf16 v[60:63], v[146:149], v[178:181], v[60:63]
	v_mfma_f32_16x16x32_bf16 v[56:59], v[154:157], v[178:181], v[56:59]
	v_mfma_f32_16x16x32_bf16 v[52:55], v[146:149], v[186:189], v[52:55]
	v_mfma_f32_16x16x32_bf16 v[44:47], v[154:157], v[186:189], v[44:47]
	v_mfma_f32_16x16x32_bf16 v[36:39], v[146:149], v[202:205], v[36:39]
	v_mfma_f32_16x16x32_bf16 v[28:31], v[154:157], v[202:205], v[28:31]
	v_mfma_f32_16x16x32_bf16 v[20:23], v[146:149], v[214:217], v[20:23]
	v_mfma_f32_16x16x32_bf16 v[12:15], v[154:157], v[214:217], v[12:15]
	v_mfma_f32_16x16x32_bf16 v[60:63], v[150:153], v[182:185], v[60:63]
	v_mfma_f32_16x16x32_bf16 v[56:59], v[158:161], v[182:185], v[56:59]
	v_mfma_f32_16x16x32_bf16 v[52:55], v[150:153], v[190:193], v[52:55]
	v_mfma_f32_16x16x32_bf16 v[44:47], v[158:161], v[190:193], v[44:47]
	v_mfma_f32_16x16x32_bf16 v[36:39], v[150:153], v[206:209], v[36:39]
	v_mfma_f32_16x16x32_bf16 v[28:31], v[158:161], v[206:209], v[28:31]
	v_mfma_f32_16x16x32_bf16 v[20:23], v[150:153], v[218:221], v[20:23]
	v_mfma_f32_16x16x32_bf16 v[12:15], v[158:161], v[218:221], v[12:15]
	s_setprio 0
	s_setprio 1
	v_mfma_f32_16x16x32_bf16 v[48:51], v[162:165], v[178:181], v[48:51]
	v_mfma_f32_16x16x32_bf16 v[40:43], v[170:173], v[178:181], v[40:43]
	v_mfma_f32_16x16x32_bf16 v[32:35], v[162:165], v[186:189], v[32:35]
	v_mfma_f32_16x16x32_bf16 v[24:27], v[170:173], v[186:189], v[24:27]
	v_mfma_f32_16x16x32_bf16 v[16:19], v[162:165], v[202:205], v[16:19]
	v_mfma_f32_16x16x32_bf16 v[8:11], v[170:173], v[202:205], v[8:11]
	v_mfma_f32_16x16x32_bf16 v[4:7], v[162:165], v[214:217], v[4:7]
	v_mfma_f32_16x16x32_bf16 v[0:3], v[170:173], v[214:217], v[0:3]
	v_mfma_f32_16x16x32_bf16 v[48:51], v[166:169], v[182:185], v[48:51]
	v_mfma_f32_16x16x32_bf16 v[40:43], v[174:177], v[182:185], v[40:43]
	v_mfma_f32_16x16x32_bf16 v[32:35], v[166:169], v[190:193], v[32:35]
	v_mfma_f32_16x16x32_bf16 v[24:27], v[174:177], v[190:193], v[24:27]
	v_mfma_f32_16x16x32_bf16 v[16:19], v[166:169], v[206:209], v[16:19]
	v_mfma_f32_16x16x32_bf16 v[8:11], v[174:177], v[206:209], v[8:11]
	v_mfma_f32_16x16x32_bf16 v[4:7], v[166:169], v[218:221], v[4:7]
	v_mfma_f32_16x16x32_bf16 v[0:3], v[174:177], v[218:221], v[0:3]
	s_setprio 0
	s_barrier
	s_add_i32 s2, s2, 2
	s_add_u32 s42, s42, 0x100
	s_addc_u32 s43, s43, 0
	s_add_u32 s53, s53, 0x100
	s_addc_u32 s54, s54, 0
	s_cmp_gt_u32 s2, 5
	s_cbranch_scc0 .LBB0_717
	v_readlane_b32 s54, v254, 56
	s_and_b64 vcc, exec, s[10:11]
	v_readlane_b32 s55, v254, 57
	s_cbranch_vccz .LBB0_720
	s_barrier

.LBB0_973:
	s_add_u32 s6, s34, s2
	s_addc_u32 s13, s35, 0
	s_add_u32 s3, s6, 0x100
	s_addc_u32 s23, s13, 0
	s_and_b64 s[36:37], s[60:61], exec
	s_cselect_b32 s73, s43, s23
	s_cselect_b32 s72, s42, s3
	s_add_u32 s2, s24, s2
	s_addc_u32 s3, s25, 0
	s_add_u32 s23, s2, 0x100
	s_addc_u32 s36, s3, 0
	s_add_i32 s47, 0, 0x10000
	s_and_b64 s[2:3], s[60:61], exec
	s_cselect_b32 s75, s53, s36
	s_cselect_b32 s74, s52, s23
	s_add_i32 s49, 0, 0x14000
	s_add_u32 s86, s6, 0x80080
	s_addc_u32 s87, s13, 0
	s_add_i32 s40, s47, s4
	s_add_i32 m0, s5, 0xc000
	s_add_i32 s51, s5, 0xe000
	s_add_i32 s23, s40, 0x2000
	s_add_u32 s82, s74, 0x80000
	v_add_u32_e32 v148, s47, v132
	v_add_u32_e32 v164, s49, v132
	s_addc_u32 s83, s75, 0
	s_add_i32 s37, s49, s4
	ds_read_b128 v[136:139], v148
	ds_read_b128 v[140:143], v148 offset:1024
	ds_read_b128 v[144:147], v148 offset:2048
	ds_read_b128 v[148:151], v148 offset:3072
	ds_read_b128 v[152:155], v164
	ds_read_b128 v[156:159], v164 offset:1024
	ds_read_b128 v[160:163], v164 offset:2048
	ds_read_b128 v[164:167], v164 offset:3072
	s_add_i32 s36, s37, 0x2000
	s_add_i32 s13, 0, 0x18000
	s_add_i32 s6, 0, 0x1c000
	s_add_u32 s62, s72, 0x80000
	s_addc_u32 s63, s73, 0
	s_add_i32 s3, s13, s4
	s_add_i32 s2, s3, 0x2000
	s_add_u32 s60, s74, 0x80080
	s_addc_u32 s61, s75, 0
	s_add_i32 s49, s6, s4
	s_add_i32 s47, s49, 0x2000
	v_lshl_add_u64 v[198:199], s[86:87], 0, v[96:97]
	ds_read_b128 v[168:171], v135
	ds_read_b128 v[172:175], v135 offset:1024
	ds_read_b128 v[176:179], v135 offset:2048
	ds_read_b128 v[180:183], v135 offset:3072
	ds_read_b128 v[184:187], v135 offset:4096
	ds_read_b128 v[188:191], v135 offset:5120
	ds_read_b128 v[192:195], v135 offset:6144
	ds_read_b128 v[202:205], v135 offset:7168
	global_load_lds_dwordx4 v[198:199], off
	v_lshl_add_u64 v[198:199], s[86:87], 0, v[130:131]
	s_mov_b32 m0, s51
	s_nop 0
	global_load_lds_dwordx4 v[198:199], off
	s_waitcnt vmcnt(8)
	s_waitcnt lgkmcnt(0)
	s_barrier
	s_setprio 1
	s_waitcnt lgkmcnt(0)
	v_mfma_f32_16x16x32_bf16 v[126:129], v[136:139], v[168:171], v[126:129]
	v_mfma_f32_16x16x32_bf16 v[122:125], v[144:147], v[168:171], v[122:125]
	v_mfma_f32_16x16x32_bf16 v[118:121], v[136:139], v[176:179], v[118:121]
	v_mfma_f32_16x16x32_bf16 v[114:117], v[144:147], v[176:179], v[114:117]
	v_mfma_f32_16x16x32_bf16 v[106:109], v[136:139], v[184:187], v[106:109]
	v_mfma_f32_16x16x32_bf16 v[98:101], v[144:147], v[184:187], v[98:101]
	v_mfma_f32_16x16x32_bf16 v[88:91], v[136:139], v[192:195], v[88:91]
	v_mfma_f32_16x16x32_bf16 v[80:83], v[144:147], v[192:195], v[80:83]
	v_mfma_f32_16x16x32_bf16 v[126:129], v[140:143], v[172:175], v[126:129]
	v_mfma_f32_16x16x32_bf16 v[122:125], v[148:151], v[172:175], v[122:125]
	v_mfma_f32_16x16x32_bf16 v[118:121], v[140:143], v[180:183], v[118:121]
	v_mfma_f32_16x16x32_bf16 v[114:117], v[148:151], v[180:183], v[114:117]
	v_mfma_f32_16x16x32_bf16 v[106:109], v[140:143], v[188:191], v[106:109]
	v_mfma_f32_16x16x32_bf16 v[98:101], v[148:151], v[188:191], v[98:101]
	v_mfma_f32_16x16x32_bf16 v[88:91], v[140:143], v[202:205], v[88:91]
	v_mfma_f32_16x16x32_bf16 v[80:83], v[148:151], v[202:205], v[80:83]
	s_setprio 0
	s_setprio 1
	v_mfma_f32_16x16x32_bf16 v[110:113], v[152:155], v[168:171], v[110:113]
	v_mfma_f32_16x16x32_bf16 v[102:105], v[160:163], v[168:171], v[102:105]
	v_mfma_f32_16x16x32_bf16 v[92:95], v[152:155], v[176:179], v[92:95]
	v_mfma_f32_16x16x32_bf16 v[84:87], v[160:163], v[176:179], v[84:87]
	v_mfma_f32_16x16x32_bf16 v[76:79], v[152:155], v[184:187], v[76:79]
	v_mfma_f32_16x16x32_bf16 v[72:75], v[160:163], v[184:187], v[72:75]
	v_mfma_f32_16x16x32_bf16 v[68:71], v[152:155], v[192:195], v[68:71]
	v_mfma_f32_16x16x32_bf16 v[64:67], v[160:163], v[192:195], v[64:67]
	v_mfma_f32_16x16x32_bf16 v[110:113], v[156:159], v[172:175], v[110:113]
	v_mfma_f32_16x16x32_bf16 v[102:105], v[164:167], v[172:175], v[102:105]
	v_mfma_f32_16x16x32_bf16 v[92:95], v[156:159], v[180:183], v[92:95]
	v_mfma_f32_16x16x32_bf16 v[84:87], v[164:167], v[180:183], v[84:87]
	v_mfma_f32_16x16x32_bf16 v[76:79], v[156:159], v[188:191], v[76:79]
	v_mfma_f32_16x16x32_bf16 v[72:75], v[164:167], v[188:191], v[72:75]
	v_mfma_f32_16x16x32_bf16 v[68:71], v[156:159], v[202:205], v[68:71]
	v_mfma_f32_16x16x32_bf16 v[64:67], v[164:167], v[202:205], v[64:67]
	s_setprio 0
	s_barrier
	s_mov_b32 m0, s40
	v_lshl_add_u64 v[198:199], s[74:75], 0, v[96:97]
	ds_read_b128 v[168:171], v135 offset:16384
	ds_read_b128 v[172:175], v135 offset:17408
	ds_read_b128 v[176:179], v135 offset:18432
	ds_read_b128 v[180:183], v135 offset:19456
	ds_read_b128 v[184:187], v135 offset:20480
	ds_read_b128 v[188:191], v135 offset:21504
	ds_read_b128 v[192:195], v135 offset:22528
	ds_read_b128 v[202:205], v135 offset:23552
	global_load_lds_dwordx4 v[198:199], off nt
	v_lshl_add_u64 v[200:201], s[74:75], 0, v[130:131]
	s_mov_b32 m0, s23
	v_lshl_add_u64 v[206:207], s[82:83], 0, v[96:97]
	global_load_lds_dwordx4 v[200:201], off nt
	s_mov_b32 m0, s37
	v_lshl_add_u64 v[208:209], s[72:73], 0, v[130:131]
	global_load_lds_dwordx4 v[206:207], off nt
	v_lshl_add_u64 v[206:207], s[82:83], 0, v[130:131]
	s_mov_b32 m0, s36
	s_nop 0
	global_load_lds_dwordx4 v[206:207], off nt
	v_lshl_add_u64 v[206:207], s[72:73], 0, v[96:97]
	s_mov_b32 m0, s5
	s_nop 0
	global_load_lds_dwordx4 v[206:207], off
	s_mov_b32 m0, s7
	s_nop 0
	global_load_lds_dwordx4 v[208:209], off
	s_waitcnt vmcnt(8)
	s_waitcnt lgkmcnt(0)
	s_barrier
	s_setprio 1
	s_waitcnt lgkmcnt(0)
	v_mfma_f32_16x16x32_bf16 v[60:63], v[136:139], v[168:171], v[60:63]
	v_mfma_f32_16x16x32_bf16 v[56:59], v[144:147], v[168:171], v[56:59]
	v_mfma_f32_16x16x32_bf16 v[52:55], v[136:139], v[176:179], v[52:55]
	v_mfma_f32_16x16x32_bf16 v[48:51], v[144:147], v[176:179], v[48:51]
	v_mfma_f32_16x16x32_bf16 v[36:39], v[136:139], v[184:187], v[36:39]
	v_mfma_f32_16x16x32_bf16 v[32:35], v[144:147], v[184:187], v[32:35]
	v_mfma_f32_16x16x32_bf16 v[20:23], v[136:139], v[192:195], v[20:23]
	v_mfma_f32_16x16x32_bf16 v[16:19], v[144:147], v[192:195], v[16:19]
	v_mfma_f32_16x16x32_bf16 v[60:63], v[140:143], v[172:175], v[60:63]
	v_mfma_f32_16x16x32_bf16 v[56:59], v[148:151], v[172:175], v[56:59]
	v_mfma_f32_16x16x32_bf16 v[52:55], v[140:143], v[180:183], v[52:55]
	v_mfma_f32_16x16x32_bf16 v[48:51], v[148:151], v[180:183], v[48:51]
	v_mfma_f32_16x16x32_bf16 v[36:39], v[140:143], v[188:191], v[36:39]
	v_mfma_f32_16x16x32_bf16 v[32:35], v[148:151], v[188:191], v[32:35]
	v_mfma_f32_16x16x32_bf16 v[20:23], v[140:143], v[202:205], v[20:23]
	v_mfma_f32_16x16x32_bf16 v[16:19], v[148:151], v[202:205], v[16:19]
	s_setprio 0
	s_setprio 1
	v_mfma_f32_16x16x32_bf16 v[44:47], v[152:155], v[168:171], v[44:47]
	v_mfma_f32_16x16x32_bf16 v[40:43], v[160:163], v[168:171], v[40:43]
	v_mfma_f32_16x16x32_bf16 v[28:31], v[152:155], v[176:179], v[28:31]
	v_mfma_f32_16x16x32_bf16 v[24:27], v[160:163], v[176:179], v[24:27]
	v_mfma_f32_16x16x32_bf16 v[12:15], v[152:155], v[184:187], v[12:15]
	v_mfma_f32_16x16x32_bf16 v[8:11], v[160:163], v[184:187], v[8:11]
	v_mfma_f32_16x16x32_bf16 v[4:7], v[152:155], v[192:195], v[4:7]
	v_mfma_f32_16x16x32_bf16 v[0:3], v[160:163], v[192:195], v[0:3]
	v_mfma_f32_16x16x32_bf16 v[44:47], v[156:159], v[172:175], v[44:47]
	v_mfma_f32_16x16x32_bf16 v[40:43], v[164:167], v[172:175], v[40:43]
	v_mfma_f32_16x16x32_bf16 v[28:31], v[156:159], v[180:183], v[28:31]
	v_mfma_f32_16x16x32_bf16 v[24:27], v[164:167], v[180:183], v[24:27]
	v_mfma_f32_16x16x32_bf16 v[12:15], v[156:159], v[188:191], v[12:15]
	v_mfma_f32_16x16x32_bf16 v[8:11], v[164:167], v[188:191], v[8:11]
	v_mfma_f32_16x16x32_bf16 v[4:7], v[156:159], v[202:205], v[4:7]
	v_mfma_f32_16x16x32_bf16 v[0:3], v[164:167], v[202:205], v[0:3]
	s_setprio 0
	s_barrier
	v_add_u32_e32 v148, s13, v132
	v_add_u32_e32 v164, s6, v132
	ds_read_b128 v[136:139], v148
	ds_read_b128 v[140:143], v148 offset:1024
	ds_read_b128 v[144:147], v148 offset:2048
	ds_read_b128 v[148:151], v148 offset:3072
	ds_read_b128 v[152:155], v164
	ds_read_b128 v[156:159], v164 offset:1024
	ds_read_b128 v[160:163], v164 offset:2048
	ds_read_b128 v[164:167], v164 offset:3072
	s_mov_b32 m0, s15
	v_lshl_add_u64 v[214:215], s[62:63], 0, v[96:97]
	ds_read_b128 v[168:171], v135 offset:32768
	ds_read_b128 v[172:175], v135 offset:33792
	ds_read_b128 v[176:179], v135 offset:34816
	ds_read_b128 v[180:183], v135 offset:35840
	ds_read_b128 v[184:187], v135 offset:36864
	ds_read_b128 v[188:191], v135 offset:37888
	ds_read_b128 v[192:195], v135 offset:38912
	ds_read_b128 v[202:205], v135 offset:39936
	global_load_lds_dwordx4 v[214:215], off
	v_lshl_add_u64 v[214:215], s[62:63], 0, v[130:131]
	s_mov_b32 m0, s17
	s_nop 0
	global_load_lds_dwordx4 v[214:215], off
	s_waitcnt vmcnt(8)
	s_waitcnt lgkmcnt(0)
	s_barrier
	s_setprio 1
	s_waitcnt lgkmcnt(0)
	v_mfma_f32_16x16x32_bf16 v[126:129], v[136:139], v[168:171], v[126:129]
	v_mfma_f32_16x16x32_bf16 v[122:125], v[144:147], v[168:171], v[122:125]
	v_mfma_f32_16x16x32_bf16 v[118:121], v[136:139], v[176:179], v[118:121]
	v_mfma_f32_16x16x32_bf16 v[114:117], v[144:147], v[176:179], v[114:117]
	v_mfma_f32_16x16x32_bf16 v[106:109], v[136:139], v[184:187], v[106:109]
	v_mfma_f32_16x16x32_bf16 v[98:101], v[144:147], v[184:187], v[98:101]
	v_mfma_f32_16x16x32_bf16 v[88:91], v[136:139], v[192:195], v[88:91]
	v_mfma_f32_16x16x32_bf16 v[80:83], v[144:147], v[192:195], v[80:83]
	v_mfma_f32_16x16x32_bf16 v[126:129], v[140:143], v[172:175], v[126:129]
	v_mfma_f32_16x16x32_bf16 v[122:125], v[148:151], v[172:175], v[122:125]
	v_mfma_f32_16x16x32_bf16 v[118:121], v[140:143], v[180:183], v[118:121]
	v_mfma_f32_16x16x32_bf16 v[114:117], v[148:151], v[180:183], v[114:117]
	v_mfma_f32_16x16x32_bf16 v[106:109], v[140:143], v[188:191], v[106:109]
	v_mfma_f32_16x16x32_bf16 v[98:101], v[148:151], v[188:191], v[98:101]
	v_mfma_f32_16x16x32_bf16 v[88:91], v[140:143], v[202:205], v[88:91]
	v_mfma_f32_16x16x32_bf16 v[80:83], v[148:151], v[202:205], v[80:83]
	s_setprio 0
	s_setprio 1
	v_mfma_f32_16x16x32_bf16 v[110:113], v[152:155], v[168:171], v[110:113]
	v_mfma_f32_16x16x32_bf16 v[102:105], v[160:163], v[168:171], v[102:105]
	v_mfma_f32_16x16x32_bf16 v[92:95], v[152:155], v[176:179], v[92:95]
	v_mfma_f32_16x16x32_bf16 v[84:87], v[160:163], v[176:179], v[84:87]
	v_mfma_f32_16x16x32_bf16 v[76:79], v[152:155], v[184:187], v[76:79]
	v_mfma_f32_16x16x32_bf16 v[72:75], v[160:163], v[184:187], v[72:75]
	v_mfma_f32_16x16x32_bf16 v[68:71], v[152:155], v[192:195], v[68:71]
	v_mfma_f32_16x16x32_bf16 v[64:67], v[160:163], v[192:195], v[64:67]
	v_mfma_f32_16x16x32_bf16 v[110:113], v[156:159], v[172:175], v[110:113]
	v_mfma_f32_16x16x32_bf16 v[102:105], v[164:167], v[172:175], v[102:105]
	v_mfma_f32_16x16x32_bf16 v[92:95], v[156:159], v[180:183], v[92:95]
	v_mfma_f32_16x16x32_bf16 v[84:87], v[164:167], v[180:183], v[84:87]
	v_mfma_f32_16x16x32_bf16 v[76:79], v[156:159], v[188:191], v[76:79]
	v_mfma_f32_16x16x32_bf16 v[72:75], v[164:167], v[188:191], v[72:75]
	v_mfma_f32_16x16x32_bf16 v[68:71], v[156:159], v[202:205], v[68:71]
	v_mfma_f32_16x16x32_bf16 v[64:67], v[164:167], v[202:205], v[64:67]
	s_setprio 0
	s_barrier
	s_mov_b32 m0, s3
	v_lshl_add_u64 v[198:199], v[198:199], 0, s[30:31]
	ds_read_b128 v[168:171], v135 offset:49152
	ds_read_b128 v[172:175], v135 offset:50176
	ds_read_b128 v[176:179], v135 offset:51200
	ds_read_b128 v[180:183], v135 offset:52224
	ds_read_b128 v[184:187], v135 offset:53248
	ds_read_b128 v[188:191], v135 offset:54272
	ds_read_b128 v[192:195], v135 offset:55296
	ds_read_b128 v[202:205], v135 offset:56320
	global_load_lds_dwordx4 v[198:199], off nt
	v_lshl_add_u64 v[198:199], v[200:201], 0, s[30:31]
	s_mov_b32 m0, s2
	s_nop 0
	global_load_lds_dwordx4 v[198:199], off nt
	v_lshl_add_u64 v[198:199], s[60:61], 0, v[96:97]
	s_mov_b32 m0, s49
	s_nop 0
	global_load_lds_dwordx4 v[198:199], off nt
	v_lshl_add_u64 v[198:199], s[60:61], 0, v[130:131]
	s_mov_b32 m0, s47
	s_nop 0
	global_load_lds_dwordx4 v[198:199], off nt
	v_lshl_add_u64 v[198:199], v[206:207], 0, s[30:31]
	s_mov_b32 m0, s18
	s_nop 0
	global_load_lds_dwordx4 v[198:199], off
	v_lshl_add_u64 v[198:199], v[208:209], 0, s[30:31]
	s_mov_b32 m0, s19
	s_nop 0
	global_load_lds_dwordx4 v[198:199], off
	s_waitcnt vmcnt(8)
	s_waitcnt lgkmcnt(0)
	s_barrier
	s_setprio 1
	s_waitcnt lgkmcnt(0)
	v_mfma_f32_16x16x32_bf16 v[60:63], v[136:139], v[168:171], v[60:63]
	v_mfma_f32_16x16x32_bf16 v[56:59], v[144:147], v[168:171], v[56:59]
	v_mfma_f32_16x16x32_bf16 v[52:55], v[136:139], v[176:179], v[52:55]
	v_mfma_f32_16x16x32_bf16 v[48:51], v[144:147], v[176:179], v[48:51]
	v_mfma_f32_16x16x32_bf16 v[36:39], v[136:139], v[184:187], v[36:39]
	v_mfma_f32_16x16x32_bf16 v[32:35], v[144:147], v[184:187], v[32:35]
	v_mfma_f32_16x16x32_bf16 v[20:23], v[136:139], v[192:195], v[20:23]
	v_mfma_f32_16x16x32_bf16 v[16:19], v[144:147], v[192:195], v[16:19]
	v_mfma_f32_16x16x32_bf16 v[60:63], v[140:143], v[172:175], v[60:63]
	v_mfma_f32_16x16x32_bf16 v[56:59], v[148:151], v[172:175], v[56:59]
	v_mfma_f32_16x16x32_bf16 v[52:55], v[140:143], v[180:183], v[52:55]
	v_mfma_f32_16x16x32_bf16 v[48:51], v[148:151], v[180:183], v[48:51]
	v_mfma_f32_16x16x32_bf16 v[36:39], v[140:143], v[188:191], v[36:39]
	v_mfma_f32_16x16x32_bf16 v[32:35], v[148:151], v[188:191], v[32:35]
	v_mfma_f32_16x16x32_bf16 v[20:23], v[140:143], v[202:205], v[20:23]
	v_mfma_f32_16x16x32_bf16 v[16:19], v[148:151], v[202:205], v[16:19]
	s_setprio 0
	s_setprio 1
	v_mfma_f32_16x16x32_bf16 v[44:47], v[152:155], v[168:171], v[44:47]
	v_mfma_f32_16x16x32_bf16 v[40:43], v[160:163], v[168:171], v[40:43]
	v_mfma_f32_16x16x32_bf16 v[28:31], v[152:155], v[176:179], v[28:31]
	v_mfma_f32_16x16x32_bf16 v[24:27], v[160:163], v[176:179], v[24:27]
	v_mfma_f32_16x16x32_bf16 v[12:15], v[152:155], v[184:187], v[12:15]
	v_mfma_f32_16x16x32_bf16 v[8:11], v[160:163], v[184:187], v[8:11]
	v_mfma_f32_16x16x32_bf16 v[4:7], v[152:155], v[192:195], v[4:7]
	v_mfma_f32_16x16x32_bf16 v[0:3], v[160:163], v[192:195], v[0:3]
	v_mfma_f32_16x16x32_bf16 v[44:47], v[156:159], v[172:175], v[44:47]
	v_mfma_f32_16x16x32_bf16 v[40:43], v[164:167], v[172:175], v[40:43]
	v_mfma_f32_16x16x32_bf16 v[28:31], v[156:159], v[180:183], v[28:31]
	v_mfma_f32_16x16x32_bf16 v[24:27], v[164:167], v[180:183], v[24:27]
	v_mfma_f32_16x16x32_bf16 v[12:15], v[156:159], v[188:191], v[12:15]
	v_mfma_f32_16x16x32_bf16 v[8:11], v[164:167], v[188:191], v[8:11]
	v_mfma_f32_16x16x32_bf16 v[4:7], v[156:159], v[202:205], v[4:7]
	v_mfma_f32_16x16x32_bf16 v[0:3], v[164:167], v[202:205], v[0:3]
	s_setprio 0
	s_barrier
	s_movk_i32 s2, 0x100
	s_andn2_b64 vcc, exec, s[58:59]
	s_mov_b64 s[60:61], -1
	s_mov_b64 s[58:59], 0
	s_cbranch_vccz .LBB0_973
	s_and_b64 vcc, exec, s[38:39]
	s_cbranch_vccz .LBB0_976
	s_barrier

.LBB0_993:
	s_add_u32 s3, s24, s46
	s_addc_u32 s6, s25, s47
	s_add_u32 s3, s3, 0x100
	s_addc_u32 s6, s6, 0
	s_add_u32 s48, s59, s46
	s_addc_u32 s49, s60, s47
	s_add_i32 s63, 0, 0x10000
	s_cmpk_eq_i32 s46, 0xf00
	s_cselect_b32 s51, s23, s6
	s_cselect_b32 s50, s61, s3
	v_add_u32_e32 v146, s63, v144
	s_cselect_b32 s49, s15, s49
	s_cselect_b32 s48, s62, s48
	s_add_i32 s3, 0, 0x14000
	ds_read_b128 v[154:157], v146
	ds_read_b128 v[158:161], v146 offset:1024
	ds_read_b128 v[162:165], v146 offset:2048
	ds_read_b128 v[166:169], v146 offset:3072
	v_add_u32_e32 v146, s3, v144
	ds_read_b128 v[174:177], v146
	ds_read_b128 v[178:181], v146 offset:1024
	ds_read_b128 v[182:185], v146 offset:2048
	ds_read_b128 v[186:189], v146 offset:3072
	v_lshl_add_u64 v[146:147], v[140:141], 0, s[46:47]
	s_add_i32 m0, s17, 0xc000
	ds_read_b128 v[190:193], v145
	ds_read_b128 v[202:205], v145 offset:1024
	ds_read_b128 v[206:209], v145 offset:2048
	ds_read_b128 v[214:217], v145 offset:3072
	ds_read_b128 v[218:221], v145 offset:4096
	ds_read_b128 v[222:225], v145 offset:5120
	ds_read_b128 v[226:229], v145 offset:6144
	ds_read_b128 v[230:233], v145 offset:7168
	global_load_lds_dwordx4 v[146:147], off
	v_lshl_add_u64 v[146:147], v[142:143], 0, s[46:47]
	s_add_i32 m0, s17, 0xe000
	s_nop 0
	global_load_lds_dwordx4 v[146:147], off
	s_waitcnt vmcnt(8)
	s_waitcnt lgkmcnt(0)
	s_barrier
	s_setprio 1
	s_waitcnt lgkmcnt(0)
	v_mfma_f32_16x16x32_bf16 v[110:113], v[154:157], v[190:193], v[110:113]
	v_mfma_f32_16x16x32_bf16 v[106:109], v[162:165], v[190:193], v[106:109]
	v_mfma_f32_16x16x32_bf16 v[118:121], v[154:157], v[206:209], v[118:121]
	v_mfma_f32_16x16x32_bf16 v[114:117], v[162:165], v[206:209], v[114:117]
	v_mfma_f32_16x16x32_bf16 v[126:129], v[154:157], v[218:221], v[126:129]
	v_mfma_f32_16x16x32_bf16 v[122:125], v[162:165], v[218:221], v[122:125]
	v_mfma_f32_16x16x32_bf16 v[92:95], v[154:157], v[226:229], v[92:95]
	v_mfma_f32_16x16x32_bf16 v[88:91], v[162:165], v[226:229], v[88:91]
	v_mfma_f32_16x16x32_bf16 v[110:113], v[158:161], v[202:205], v[110:113]
	v_mfma_f32_16x16x32_bf16 v[106:109], v[166:169], v[202:205], v[106:109]
	v_mfma_f32_16x16x32_bf16 v[118:121], v[158:161], v[214:217], v[118:121]
	v_mfma_f32_16x16x32_bf16 v[114:117], v[166:169], v[214:217], v[114:117]
	v_mfma_f32_16x16x32_bf16 v[126:129], v[158:161], v[222:225], v[126:129]
	v_mfma_f32_16x16x32_bf16 v[122:125], v[166:169], v[222:225], v[122:125]
	v_mfma_f32_16x16x32_bf16 v[92:95], v[158:161], v[230:233], v[92:95]
	v_mfma_f32_16x16x32_bf16 v[88:91], v[166:169], v[230:233], v[88:91]
	s_setprio 0
	s_setprio 1
	v_mfma_f32_16x16x32_bf16 v[4:7], v[174:177], v[190:193], v[4:7]
	v_mfma_f32_16x16x32_bf16 v[0:3], v[182:185], v[190:193], v[0:3]
	v_mfma_f32_16x16x32_bf16 v[12:15], v[174:177], v[206:209], v[12:15]
	v_mfma_f32_16x16x32_bf16 v[8:11], v[182:185], v[206:209], v[8:11]
	v_mfma_f32_16x16x32_bf16 v[24:27], v[174:177], v[218:221], v[24:27]
	v_mfma_f32_16x16x32_bf16 v[20:23], v[182:185], v[218:221], v[20:23]
	v_mfma_f32_16x16x32_bf16 v[40:43], v[174:177], v[226:229], v[40:43]
	v_mfma_f32_16x16x32_bf16 v[32:35], v[182:185], v[226:229], v[32:35]
	v_mfma_f32_16x16x32_bf16 v[4:7], v[178:181], v[202:205], v[4:7]
	v_mfma_f32_16x16x32_bf16 v[0:3], v[186:189], v[202:205], v[0:3]
	v_mfma_f32_16x16x32_bf16 v[12:15], v[178:181], v[214:217], v[12:15]
	v_mfma_f32_16x16x32_bf16 v[8:11], v[186:189], v[214:217], v[8:11]
	v_mfma_f32_16x16x32_bf16 v[24:27], v[178:181], v[222:225], v[24:27]
	v_mfma_f32_16x16x32_bf16 v[20:23], v[186:189], v[222:225], v[20:23]
	v_mfma_f32_16x16x32_bf16 v[40:43], v[178:181], v[230:233], v[40:43]
	v_mfma_f32_16x16x32_bf16 v[32:35], v[186:189], v[230:233], v[32:35]
	s_setprio 0
	s_barrier
	s_add_i32 s6, s63, s5
	v_lshl_add_u64 v[146:147], s[48:49], 0, v[96:97]
	s_mov_b32 m0, s6
	ds_read_b128 v[190:193], v145 offset:16384
	ds_read_b128 v[202:205], v145 offset:17408
	ds_read_b128 v[206:209], v145 offset:18432
	ds_read_b128 v[214:217], v145 offset:19456
	ds_read_b128 v[218:221], v145 offset:20480
	ds_read_b128 v[222:225], v145 offset:21504
	ds_read_b128 v[226:229], v145 offset:22528
	ds_read_b128 v[230:233], v145 offset:23552
	global_load_lds_dwordx4 v[146:147], off nt
	s_add_i32 m0, s6, 0x2000
	s_add_u32 s72, s48, 0x80000
	v_lshl_add_u64 v[150:151], s[48:49], 0, v[130:131]
	s_addc_u32 s73, s49, 0
	s_add_i32 s3, s3, s5
	global_load_lds_dwordx4 v[150:151], off nt
	v_lshl_add_u64 v[170:171], s[72:73], 0, v[96:97]
	s_mov_b32 m0, s3
	v_lshl_add_u64 v[194:195], s[50:51], 0, v[132:133]
	global_load_lds_dwordx4 v[170:171], off nt
	v_lshl_add_u64 v[170:171], s[72:73], 0, v[130:131]
	s_add_i32 m0, s3, 0x2000
	s_nop 0
	global_load_lds_dwordx4 v[170:171], off nt
	v_lshl_add_u64 v[170:171], s[50:51], 0, v[134:135]
	s_mov_b32 m0, s17
	s_nop 0
	global_load_lds_dwordx4 v[170:171], off
	s_mov_b32 m0, s18
	s_nop 0
	global_load_lds_dwordx4 v[194:195], off
	s_waitcnt vmcnt(8)
	s_waitcnt lgkmcnt(0)
	s_barrier
	s_setprio 1
	s_waitcnt lgkmcnt(0)
	v_mfma_f32_16x16x32_bf16 v[102:105], v[154:157], v[190:193], v[102:105]
	v_mfma_f32_16x16x32_bf16 v[98:101], v[162:165], v[190:193], v[98:101]
	v_mfma_f32_16x16x32_bf16 v[84:87], v[154:157], v[206:209], v[84:87]
	v_mfma_f32_16x16x32_bf16 v[80:83], v[162:165], v[206:209], v[80:83]
	v_mfma_f32_16x16x32_bf16 v[68:71], v[154:157], v[218:221], v[68:71]
	v_mfma_f32_16x16x32_bf16 v[64:67], v[162:165], v[218:221], v[64:67]
	v_mfma_f32_16x16x32_bf16 v[44:47], v[154:157], v[226:229], v[44:47]
	v_mfma_f32_16x16x32_bf16 v[36:39], v[162:165], v[226:229], v[36:39]
	v_mfma_f32_16x16x32_bf16 v[102:105], v[158:161], v[202:205], v[102:105]
	v_mfma_f32_16x16x32_bf16 v[98:101], v[166:169], v[202:205], v[98:101]
	v_mfma_f32_16x16x32_bf16 v[84:87], v[158:161], v[214:217], v[84:87]
	v_mfma_f32_16x16x32_bf16 v[80:83], v[166:169], v[214:217], v[80:83]
	v_mfma_f32_16x16x32_bf16 v[68:71], v[158:161], v[222:225], v[68:71]
	v_mfma_f32_16x16x32_bf16 v[64:67], v[166:169], v[222:225], v[64:67]
	v_mfma_f32_16x16x32_bf16 v[44:47], v[158:161], v[230:233], v[44:47]
	v_mfma_f32_16x16x32_bf16 v[36:39], v[166:169], v[230:233], v[36:39]
	s_setprio 0
	s_setprio 1
	v_mfma_f32_16x16x32_bf16 v[60:63], v[174:177], v[190:193], v[60:63]
	v_mfma_f32_16x16x32_bf16 v[56:59], v[182:185], v[190:193], v[56:59]
	v_mfma_f32_16x16x32_bf16 v[76:79], v[174:177], v[206:209], v[76:79]
	v_mfma_f32_16x16x32_bf16 v[72:75], v[182:185], v[206:209], v[72:75]
	v_mfma_f32_16x16x32_bf16 v[52:55], v[174:177], v[218:221], v[52:55]
	v_mfma_f32_16x16x32_bf16 v[48:51], v[182:185], v[218:221], v[48:51]
	v_mfma_f32_16x16x32_bf16 v[28:31], v[174:177], v[226:229], v[28:31]
	v_mfma_f32_16x16x32_bf16 v[16:19], v[182:185], v[226:229], v[16:19]
	v_mfma_f32_16x16x32_bf16 v[60:63], v[178:181], v[202:205], v[60:63]
	v_mfma_f32_16x16x32_bf16 v[56:59], v[186:189], v[202:205], v[56:59]
	v_mfma_f32_16x16x32_bf16 v[76:79], v[178:181], v[214:217], v[76:79]
	v_mfma_f32_16x16x32_bf16 v[72:75], v[186:189], v[214:217], v[72:75]
	v_mfma_f32_16x16x32_bf16 v[52:55], v[178:181], v[222:225], v[52:55]
	v_mfma_f32_16x16x32_bf16 v[48:51], v[186:189], v[222:225], v[48:51]
	v_mfma_f32_16x16x32_bf16 v[28:31], v[178:181], v[230:233], v[28:31]
	v_mfma_f32_16x16x32_bf16 v[16:19], v[186:189], v[230:233], v[16:19]
	s_setprio 0
	s_barrier
	s_add_i32 s3, 0, 0x18000
	v_add_u32_e32 v149, s3, v144
	s_add_i32 s6, 0, 0x1c000
	ds_read_b128 v[154:157], v149
	ds_read_b128 v[158:161], v149 offset:1024
	ds_read_b128 v[162:165], v149 offset:2048
	ds_read_b128 v[166:169], v149 offset:3072
	v_add_u32_e32 v149, s6, v144
	ds_read_b128 v[174:177], v149
	ds_read_b128 v[178:181], v149 offset:1024
	ds_read_b128 v[182:185], v149 offset:2048
	ds_read_b128 v[186:189], v149 offset:3072
	s_add_u32 s50, s50, 0x80000
	s_addc_u32 s51, s51, 0
	s_mov_b32 m0, s19
	v_lshl_add_u64 v[198:199], s[50:51], 0, v[134:135]
	ds_read_b128 v[190:193], v145 offset:32768
	ds_read_b128 v[202:205], v145 offset:33792
	ds_read_b128 v[206:209], v145 offset:34816
	ds_read_b128 v[214:217], v145 offset:35840
	ds_read_b128 v[218:221], v145 offset:36864
	ds_read_b128 v[222:225], v145 offset:37888
	ds_read_b128 v[226:229], v145 offset:38912
	ds_read_b128 v[230:233], v145 offset:39936
	global_load_lds_dwordx4 v[198:199], off
	v_lshl_add_u64 v[198:199], s[50:51], 0, v[132:133]
	s_mov_b32 m0, s20
	s_nop 0
	global_load_lds_dwordx4 v[198:199], off
	s_waitcnt vmcnt(8)
	s_waitcnt lgkmcnt(0)
	s_barrier
	s_setprio 1
	s_waitcnt lgkmcnt(0)
	v_mfma_f32_16x16x32_bf16 v[110:113], v[154:157], v[190:193], v[110:113]
	v_mfma_f32_16x16x32_bf16 v[106:109], v[162:165], v[190:193], v[106:109]
	v_mfma_f32_16x16x32_bf16 v[118:121], v[154:157], v[206:209], v[118:121]
	v_mfma_f32_16x16x32_bf16 v[114:117], v[162:165], v[206:209], v[114:117]
	v_mfma_f32_16x16x32_bf16 v[126:129], v[154:157], v[218:221], v[126:129]
	v_mfma_f32_16x16x32_bf16 v[122:125], v[162:165], v[218:221], v[122:125]
	v_mfma_f32_16x16x32_bf16 v[92:95], v[154:157], v[226:229], v[92:95]
	v_mfma_f32_16x16x32_bf16 v[88:91], v[162:165], v[226:229], v[88:91]
	v_mfma_f32_16x16x32_bf16 v[110:113], v[158:161], v[202:205], v[110:113]
	v_mfma_f32_16x16x32_bf16 v[106:109], v[166:169], v[202:205], v[106:109]
	v_mfma_f32_16x16x32_bf16 v[118:121], v[158:161], v[214:217], v[118:121]
	v_mfma_f32_16x16x32_bf16 v[114:117], v[166:169], v[214:217], v[114:117]
	v_mfma_f32_16x16x32_bf16 v[126:129], v[158:161], v[222:225], v[126:129]
	v_mfma_f32_16x16x32_bf16 v[122:125], v[166:169], v[222:225], v[122:125]
	v_mfma_f32_16x16x32_bf16 v[92:95], v[158:161], v[230:233], v[92:95]
	v_mfma_f32_16x16x32_bf16 v[88:91], v[166:169], v[230:233], v[88:91]
	s_setprio 0
	s_setprio 1
	v_mfma_f32_16x16x32_bf16 v[4:7], v[174:177], v[190:193], v[4:7]
	v_mfma_f32_16x16x32_bf16 v[0:3], v[182:185], v[190:193], v[0:3]
	v_mfma_f32_16x16x32_bf16 v[12:15], v[174:177], v[206:209], v[12:15]
	v_mfma_f32_16x16x32_bf16 v[8:11], v[182:185], v[206:209], v[8:11]
	v_mfma_f32_16x16x32_bf16 v[24:27], v[174:177], v[218:221], v[24:27]
	v_mfma_f32_16x16x32_bf16 v[20:23], v[182:185], v[218:221], v[20:23]
	v_mfma_f32_16x16x32_bf16 v[40:43], v[174:177], v[226:229], v[40:43]
	v_mfma_f32_16x16x32_bf16 v[32:35], v[182:185], v[226:229], v[32:35]
	v_mfma_f32_16x16x32_bf16 v[4:7], v[178:181], v[202:205], v[4:7]
	v_mfma_f32_16x16x32_bf16 v[0:3], v[186:189], v[202:205], v[0:3]
	v_mfma_f32_16x16x32_bf16 v[12:15], v[178:181], v[214:217], v[12:15]
	v_mfma_f32_16x16x32_bf16 v[8:11], v[186:189], v[214:217], v[8:11]
	v_mfma_f32_16x16x32_bf16 v[24:27], v[178:181], v[222:225], v[24:27]
	v_mfma_f32_16x16x32_bf16 v[20:23], v[186:189], v[222:225], v[20:23]
	v_mfma_f32_16x16x32_bf16 v[40:43], v[178:181], v[230:233], v[40:43]
	v_mfma_f32_16x16x32_bf16 v[32:35], v[186:189], v[230:233], v[32:35]
	s_setprio 0
	s_barrier
	s_add_i32 s3, s3, s5
	v_lshl_add_u64 v[146:147], v[146:147], 0, s[30:31]
	s_mov_b32 m0, s3
	ds_read_b128 v[190:193], v145 offset:49152
	ds_read_b128 v[202:205], v145 offset:50176
	ds_read_b128 v[206:209], v145 offset:51200
	ds_read_b128 v[214:217], v145 offset:52224
	ds_read_b128 v[218:221], v145 offset:53248
	ds_read_b128 v[222:225], v145 offset:54272
	ds_read_b128 v[226:229], v145 offset:55296
	ds_read_b128 v[230:233], v145 offset:56320
	global_load_lds_dwordx4 v[146:147], off nt
	s_add_i32 m0, s3, 0x2000
	s_add_u32 s48, s48, 0x80080
	v_lshl_add_u64 v[146:147], v[150:151], 0, s[30:31]
	s_addc_u32 s49, s49, 0
	s_add_i32 s3, s6, s5
	global_load_lds_dwordx4 v[146:147], off nt
	v_lshl_add_u64 v[146:147], s[48:49], 0, v[96:97]
	s_mov_b32 m0, s3
	s_nop 0
	global_load_lds_dwordx4 v[146:147], off nt
	v_lshl_add_u64 v[146:147], s[48:49], 0, v[130:131]
	s_add_i32 m0, s3, 0x2000
	s_nop 0
	global_load_lds_dwordx4 v[146:147], off nt
	v_lshl_add_u64 v[146:147], v[170:171], 0, s[30:31]
	s_mov_b32 m0, s37
	s_nop 0
	global_load_lds_dwordx4 v[146:147], off
	v_lshl_add_u64 v[146:147], v[194:195], 0, s[30:31]
	s_mov_b32 m0, s56
	s_nop 0
	global_load_lds_dwordx4 v[146:147], off
	s_waitcnt vmcnt(8)
	s_waitcnt lgkmcnt(0)
	s_barrier
	s_setprio 1
	s_waitcnt lgkmcnt(0)
	v_mfma_f32_16x16x32_bf16 v[102:105], v[154:157], v[190:193], v[102:105]
	v_mfma_f32_16x16x32_bf16 v[98:101], v[162:165], v[190:193], v[98:101]
	v_mfma_f32_16x16x32_bf16 v[84:87], v[154:157], v[206:209], v[84:87]
	v_mfma_f32_16x16x32_bf16 v[80:83], v[162:165], v[206:209], v[80:83]
	v_mfma_f32_16x16x32_bf16 v[68:71], v[154:157], v[218:221], v[68:71]
	v_mfma_f32_16x16x32_bf16 v[64:67], v[162:165], v[218:221], v[64:67]
	v_mfma_f32_16x16x32_bf16 v[44:47], v[154:157], v[226:229], v[44:47]
	v_mfma_f32_16x16x32_bf16 v[36:39], v[162:165], v[226:229], v[36:39]
	v_mfma_f32_16x16x32_bf16 v[102:105], v[158:161], v[202:205], v[102:105]
	v_mfma_f32_16x16x32_bf16 v[98:101], v[166:169], v[202:205], v[98:101]
	v_mfma_f32_16x16x32_bf16 v[84:87], v[158:161], v[214:217], v[84:87]
	v_mfma_f32_16x16x32_bf16 v[80:83], v[166:169], v[214:217], v[80:83]
	v_mfma_f32_16x16x32_bf16 v[68:71], v[158:161], v[222:225], v[68:71]
	v_mfma_f32_16x16x32_bf16 v[64:67], v[166:169], v[222:225], v[64:67]
	v_mfma_f32_16x16x32_bf16 v[44:47], v[158:161], v[230:233], v[44:47]
	v_mfma_f32_16x16x32_bf16 v[36:39], v[166:169], v[230:233], v[36:39]
	s_setprio 0
	s_setprio 1
	v_mfma_f32_16x16x32_bf16 v[60:63], v[174:177], v[190:193], v[60:63]
	v_mfma_f32_16x16x32_bf16 v[56:59], v[182:185], v[190:193], v[56:59]
	v_mfma_f32_16x16x32_bf16 v[76:79], v[174:177], v[206:209], v[76:79]
	v_mfma_f32_16x16x32_bf16 v[72:75], v[182:185], v[206:209], v[72:75]
	v_mfma_f32_16x16x32_bf16 v[52:55], v[174:177], v[218:221], v[52:55]
	v_mfma_f32_16x16x32_bf16 v[48:51], v[182:185], v[218:221], v[48:51]
	v_mfma_f32_16x16x32_bf16 v[28:31], v[174:177], v[226:229], v[28:31]
	v_mfma_f32_16x16x32_bf16 v[16:19], v[182:185], v[226:229], v[16:19]
	v_mfma_f32_16x16x32_bf16 v[60:63], v[178:181], v[202:205], v[60:63]
	v_mfma_f32_16x16x32_bf16 v[56:59], v[186:189], v[202:205], v[56:59]
	v_mfma_f32_16x16x32_bf16 v[76:79], v[178:181], v[214:217], v[76:79]
	v_mfma_f32_16x16x32_bf16 v[72:75], v[186:189], v[214:217], v[72:75]
	v_mfma_f32_16x16x32_bf16 v[52:55], v[178:181], v[222:225], v[52:55]
	v_mfma_f32_16x16x32_bf16 v[48:51], v[186:189], v[222:225], v[48:51]
	v_mfma_f32_16x16x32_bf16 v[28:31], v[178:181], v[230:233], v[28:31]
	v_mfma_f32_16x16x32_bf16 v[16:19], v[186:189], v[230:233], v[16:19]
	s_setprio 0
	s_barrier
	s_add_i32 s2, s2, 2
	s_add_u32 s46, s46, 0x100
	s_addc_u32 s47, s47, 0
	s_cmp_gt_u32 s2, 29
	s_cbranch_scc0 .LBB0_993
	s_and_b64 vcc, exec, s[12:13]
	s_cbranch_vccz .LBB0_996
	s_barrier

.LBB0_1158:
	s_add_u32 s34, s62, 0x100
	s_addc_u32 s35, s63, 0
	s_add_i32 s67, 0, 0x10000
	s_cmp_eq_u32 s6, 28
	s_cselect_b32 s89, s23, s35
	s_cselect_b32 s88, s61, s34
	s_cselect_b32 vcc_hi, s91, s3
	s_cselect_b32 vcc_lo, s93, s2
	s_add_i32 s76, 0, 0x14000
	v_add_u32_e32 v142, s67, v191
	v_add_u32_e32 v158, s76, v191
	ds_read_b128 v[130:133], v142
	ds_read_b128 v[134:137], v142 offset:1024
	ds_read_b128 v[138:141], v142 offset:2048
	ds_read_b128 v[142:145], v142 offset:3072
	ds_read_b128 v[146:149], v158
	ds_read_b128 v[150:153], v158 offset:1024
	ds_read_b128 v[154:157], v158 offset:2048
	ds_read_b128 v[158:161], v158 offset:3072
	v_lshl_add_u64 v[188:189], s[62:63], 0, v[184:185]
	s_add_i32 m0, s17, 0xc000
	ds_read_b128 v[162:165], v224
	ds_read_b128 v[166:169], v224 offset:1024
	ds_read_b128 v[170:173], v224 offset:2048
	ds_read_b128 v[178:181], v224 offset:3072
	ds_read_b128 v[202:205], v224 offset:4096
	ds_read_b128 v[206:209], v224 offset:5120
	ds_read_b128 v[226:229], v224 offset:6144
	ds_read_b128 v[230:233], v224 offset:7168
	global_load_lds_dwordx4 v[188:189], off
	v_lshl_add_u64 v[188:189], s[62:63], 0, v[186:187]
	s_add_i32 m0, s17, 0xe000
	s_nop 0
	global_load_lds_dwordx4 v[188:189], off
	s_waitcnt vmcnt(8)
	s_waitcnt lgkmcnt(0)
	s_barrier
	s_setprio 1
	s_waitcnt lgkmcnt(0)
	v_mfma_f32_16x16x32_bf16 v[126:129], v[130:133], v[162:165], v[126:129]
	v_mfma_f32_16x16x32_bf16 v[56:59], v[138:141], v[162:165], v[56:59]
	v_mfma_f32_16x16x32_bf16 v[122:125], v[130:133], v[170:173], v[122:125]
	v_mfma_f32_16x16x32_bf16 v[52:55], v[138:141], v[170:173], v[52:55]
	v_mfma_f32_16x16x32_bf16 v[118:121], v[130:133], v[202:205], v[118:121]
	v_mfma_f32_16x16x32_bf16 v[60:63], v[138:141], v[202:205], v[60:63]
	v_mfma_f32_16x16x32_bf16 v[114:117], v[130:133], v[226:229], v[114:117]
	v_mfma_f32_16x16x32_bf16 v[44:47], v[138:141], v[226:229], v[44:47]
	v_mfma_f32_16x16x32_bf16 v[126:129], v[134:137], v[166:169], v[126:129]
	v_mfma_f32_16x16x32_bf16 v[56:59], v[142:145], v[166:169], v[56:59]
	v_mfma_f32_16x16x32_bf16 v[122:125], v[134:137], v[178:181], v[122:125]
	v_mfma_f32_16x16x32_bf16 v[52:55], v[142:145], v[178:181], v[52:55]
	v_mfma_f32_16x16x32_bf16 v[118:121], v[134:137], v[206:209], v[118:121]
	v_mfma_f32_16x16x32_bf16 v[60:63], v[142:145], v[206:209], v[60:63]
	v_mfma_f32_16x16x32_bf16 v[114:117], v[134:137], v[230:233], v[114:117]
	v_mfma_f32_16x16x32_bf16 v[44:47], v[142:145], v[230:233], v[44:47]
	s_setprio 0
	s_setprio 1
	v_mfma_f32_16x16x32_bf16 v[110:113], v[146:149], v[162:165], v[110:113]
	v_mfma_f32_16x16x32_bf16 v[40:43], v[154:157], v[162:165], v[40:43]
	v_mfma_f32_16x16x32_bf16 v[106:109], v[146:149], v[170:173], v[106:109]
	v_mfma_f32_16x16x32_bf16 v[36:39], v[154:157], v[170:173], v[36:39]
	v_mfma_f32_16x16x32_bf16 v[102:105], v[146:149], v[202:205], v[102:105]
	v_mfma_f32_16x16x32_bf16 v[48:51], v[154:157], v[202:205], v[48:51]
	v_mfma_f32_16x16x32_bf16 v[98:101], v[146:149], v[226:229], v[98:101]
	v_mfma_f32_16x16x32_bf16 v[32:35], v[154:157], v[226:229], v[32:35]
	v_mfma_f32_16x16x32_bf16 v[110:113], v[150:153], v[166:169], v[110:113]
	v_mfma_f32_16x16x32_bf16 v[40:43], v[158:161], v[166:169], v[40:43]
	v_mfma_f32_16x16x32_bf16 v[106:109], v[150:153], v[178:181], v[106:109]
	v_mfma_f32_16x16x32_bf16 v[36:39], v[158:161], v[178:181], v[36:39]
	v_mfma_f32_16x16x32_bf16 v[102:105], v[150:153], v[206:209], v[102:105]
	v_mfma_f32_16x16x32_bf16 v[48:51], v[158:161], v[206:209], v[48:51]
	v_mfma_f32_16x16x32_bf16 v[98:101], v[150:153], v[230:233], v[98:101]
	v_mfma_f32_16x16x32_bf16 v[32:35], v[158:161], v[230:233], v[32:35]
	s_setprio 0
	s_barrier
	s_add_i32 s62, s67, s5
	v_lshl_add_u64 v[188:189], vcc, 0, v[96:97]
	s_mov_b32 m0, s62
	ds_read_b128 v[162:165], v224 offset:16384
	ds_read_b128 v[166:169], v224 offset:17408
	ds_read_b128 v[170:173], v224 offset:18432
	ds_read_b128 v[178:181], v224 offset:19456
	ds_read_b128 v[202:205], v224 offset:20480
	ds_read_b128 v[206:209], v224 offset:21504
	ds_read_b128 v[226:229], v224 offset:22528
	ds_read_b128 v[230:233], v224 offset:23552
	global_load_lds_dwordx4 v[188:189], off nt
	s_add_i32 m0, s62, 0x2000
	s_add_u32 s62, vcc_lo, 0x80000
	v_lshl_add_u64 v[198:199], vcc, 0, v[182:183]
	s_addc_u32 s63, vcc_hi, 0
	s_add_i32 s67, s76, s5
	global_load_lds_dwordx4 v[198:199], off nt
	v_lshl_add_u64 v[200:201], s[62:63], 0, v[96:97]
	s_mov_b32 m0, s67
	v_lshl_add_u64 v[234:235], s[88:89], 0, v[176:177]
	global_load_lds_dwordx4 v[200:201], off nt
	v_lshl_add_u64 v[200:201], s[62:63], 0, v[182:183]
	s_add_i32 m0, s67, 0x2000
	s_nop 0
	global_load_lds_dwordx4 v[200:201], off nt
	v_lshl_add_u64 v[200:201], s[88:89], 0, v[174:175]
	s_mov_b32 m0, s17
	s_nop 0
	global_load_lds_dwordx4 v[200:201], off
	s_mov_b32 m0, s18
	s_nop 0
	global_load_lds_dwordx4 v[234:235], off
	s_waitcnt vmcnt(8)
	s_waitcnt lgkmcnt(0)
	s_barrier
	s_setprio 1
	s_waitcnt lgkmcnt(0)
	v_mfma_f32_16x16x32_bf16 v[92:95], v[130:133], v[162:165], v[92:95]
	v_mfma_f32_16x16x32_bf16 v[24:27], v[138:141], v[162:165], v[24:27]
	v_mfma_f32_16x16x32_bf16 v[88:91], v[130:133], v[170:173], v[88:91]
	v_mfma_f32_16x16x32_bf16 v[28:31], v[138:141], v[170:173], v[28:31]
	v_mfma_f32_16x16x32_bf16 v[84:87], v[130:133], v[202:205], v[84:87]
	v_mfma_f32_16x16x32_bf16 v[16:19], v[138:141], v[202:205], v[16:19]
	v_mfma_f32_16x16x32_bf16 v[80:83], v[130:133], v[226:229], v[80:83]
	v_mfma_f32_16x16x32_bf16 v[20:23], v[138:141], v[226:229], v[20:23]
	v_mfma_f32_16x16x32_bf16 v[92:95], v[134:137], v[166:169], v[92:95]
	v_mfma_f32_16x16x32_bf16 v[24:27], v[142:145], v[166:169], v[24:27]
	v_mfma_f32_16x16x32_bf16 v[88:91], v[134:137], v[178:181], v[88:91]
	v_mfma_f32_16x16x32_bf16 v[28:31], v[142:145], v[178:181], v[28:31]
	v_mfma_f32_16x16x32_bf16 v[84:87], v[134:137], v[206:209], v[84:87]
	v_mfma_f32_16x16x32_bf16 v[16:19], v[142:145], v[206:209], v[16:19]
	v_mfma_f32_16x16x32_bf16 v[80:83], v[134:137], v[230:233], v[80:83]
	v_mfma_f32_16x16x32_bf16 v[20:23], v[142:145], v[230:233], v[20:23]
	s_setprio 0
	s_setprio 1
	v_mfma_f32_16x16x32_bf16 v[76:79], v[146:149], v[162:165], v[76:79]
	v_mfma_f32_16x16x32_bf16 v[12:15], v[154:157], v[162:165], v[12:15]
	v_mfma_f32_16x16x32_bf16 v[72:75], v[146:149], v[170:173], v[72:75]
	v_mfma_f32_16x16x32_bf16 v[8:11], v[154:157], v[170:173], v[8:11]
	v_mfma_f32_16x16x32_bf16 v[68:71], v[146:149], v[202:205], v[68:71]
	v_mfma_f32_16x16x32_bf16 v[0:3], v[154:157], v[202:205], v[0:3]
	v_mfma_f32_16x16x32_bf16 v[64:67], v[146:149], v[226:229], v[64:67]
	v_mfma_f32_16x16x32_bf16 v[4:7], v[154:157], v[226:229], v[4:7]
	v_mfma_f32_16x16x32_bf16 v[76:79], v[150:153], v[166:169], v[76:79]
	v_mfma_f32_16x16x32_bf16 v[12:15], v[158:161], v[166:169], v[12:15]
	v_mfma_f32_16x16x32_bf16 v[72:75], v[150:153], v[178:181], v[72:75]
	v_mfma_f32_16x16x32_bf16 v[8:11], v[158:161], v[178:181], v[8:11]
	v_mfma_f32_16x16x32_bf16 v[68:71], v[150:153], v[206:209], v[68:71]
	v_mfma_f32_16x16x32_bf16 v[0:3], v[158:161], v[206:209], v[0:3]
	v_mfma_f32_16x16x32_bf16 v[64:67], v[150:153], v[230:233], v[64:67]
	v_mfma_f32_16x16x32_bf16 v[4:7], v[158:161], v[230:233], v[4:7]
	s_setprio 0
	s_barrier
	s_add_i32 s67, 0, 0x18000
	s_add_i32 s76, 0, 0x1c000
	v_add_u32_e32 v142, s67, v191
	v_add_u32_e32 v158, s76, v191
	ds_read_b128 v[130:133], v142
	ds_read_b128 v[134:137], v142 offset:1024
	ds_read_b128 v[138:141], v142 offset:2048
	ds_read_b128 v[142:145], v142 offset:3072
	ds_read_b128 v[146:149], v158
	ds_read_b128 v[150:153], v158 offset:1024
	ds_read_b128 v[154:157], v158 offset:2048
	ds_read_b128 v[158:161], v158 offset:3072
	s_add_u32 s62, s88, 0x80000
	s_addc_u32 s63, s89, 0
	s_mov_b32 m0, s19
	v_lshl_add_u64 v[236:237], s[62:63], 0, v[174:175]
	ds_read_b128 v[162:165], v224 offset:32768
	ds_read_b128 v[166:169], v224 offset:33792
	ds_read_b128 v[170:173], v224 offset:34816
	ds_read_b128 v[178:181], v224 offset:35840
	ds_read_b128 v[202:205], v224 offset:36864
	ds_read_b128 v[206:209], v224 offset:37888
	ds_read_b128 v[226:229], v224 offset:38912
	ds_read_b128 v[230:233], v224 offset:39936
	global_load_lds_dwordx4 v[236:237], off
	v_lshl_add_u64 v[236:237], s[62:63], 0, v[176:177]
	s_mov_b32 m0, s20
	s_nop 0
	global_load_lds_dwordx4 v[236:237], off
	s_waitcnt vmcnt(8)
	s_waitcnt lgkmcnt(0)
	s_barrier
	s_setprio 1
	s_waitcnt lgkmcnt(0)
	v_mfma_f32_16x16x32_bf16 v[126:129], v[130:133], v[162:165], v[126:129]
	v_mfma_f32_16x16x32_bf16 v[56:59], v[138:141], v[162:165], v[56:59]
	v_mfma_f32_16x16x32_bf16 v[122:125], v[130:133], v[170:173], v[122:125]
	v_mfma_f32_16x16x32_bf16 v[52:55], v[138:141], v[170:173], v[52:55]
	v_mfma_f32_16x16x32_bf16 v[118:121], v[130:133], v[202:205], v[118:121]
	v_mfma_f32_16x16x32_bf16 v[60:63], v[138:141], v[202:205], v[60:63]
	v_mfma_f32_16x16x32_bf16 v[114:117], v[130:133], v[226:229], v[114:117]
	v_mfma_f32_16x16x32_bf16 v[44:47], v[138:141], v[226:229], v[44:47]
	v_mfma_f32_16x16x32_bf16 v[126:129], v[134:137], v[166:169], v[126:129]
	v_mfma_f32_16x16x32_bf16 v[56:59], v[142:145], v[166:169], v[56:59]
	v_mfma_f32_16x16x32_bf16 v[122:125], v[134:137], v[178:181], v[122:125]
	v_mfma_f32_16x16x32_bf16 v[52:55], v[142:145], v[178:181], v[52:55]
	v_mfma_f32_16x16x32_bf16 v[118:121], v[134:137], v[206:209], v[118:121]
	v_mfma_f32_16x16x32_bf16 v[60:63], v[142:145], v[206:209], v[60:63]
	v_mfma_f32_16x16x32_bf16 v[114:117], v[134:137], v[230:233], v[114:117]
	v_mfma_f32_16x16x32_bf16 v[44:47], v[142:145], v[230:233], v[44:47]
	s_setprio 0
	s_setprio 1
	v_mfma_f32_16x16x32_bf16 v[110:113], v[146:149], v[162:165], v[110:113]
	v_mfma_f32_16x16x32_bf16 v[40:43], v[154:157], v[162:165], v[40:43]
	v_mfma_f32_16x16x32_bf16 v[106:109], v[146:149], v[170:173], v[106:109]
	v_mfma_f32_16x16x32_bf16 v[36:39], v[154:157], v[170:173], v[36:39]
	v_mfma_f32_16x16x32_bf16 v[102:105], v[146:149], v[202:205], v[102:105]
	v_mfma_f32_16x16x32_bf16 v[48:51], v[154:157], v[202:205], v[48:51]
	v_mfma_f32_16x16x32_bf16 v[98:101], v[146:149], v[226:229], v[98:101]
	v_mfma_f32_16x16x32_bf16 v[32:35], v[154:157], v[226:229], v[32:35]
	v_mfma_f32_16x16x32_bf16 v[110:113], v[150:153], v[166:169], v[110:113]
	v_mfma_f32_16x16x32_bf16 v[40:43], v[158:161], v[166:169], v[40:43]
	v_mfma_f32_16x16x32_bf16 v[106:109], v[150:153], v[178:181], v[106:109]
	v_mfma_f32_16x16x32_bf16 v[36:39], v[158:161], v[178:181], v[36:39]
	v_mfma_f32_16x16x32_bf16 v[102:105], v[150:153], v[206:209], v[102:105]
	v_mfma_f32_16x16x32_bf16 v[48:51], v[158:161], v[206:209], v[48:51]
	v_mfma_f32_16x16x32_bf16 v[98:101], v[150:153], v[230:233], v[98:101]
	v_mfma_f32_16x16x32_bf16 v[32:35], v[158:161], v[230:233], v[32:35]
	s_setprio 0
	s_barrier
	s_add_i32 s62, s67, s5
	v_lshl_add_u64 v[188:189], v[188:189], 0, s[30:31]
	s_mov_b32 m0, s62
	ds_read_b128 v[162:165], v224 offset:49152
	ds_read_b128 v[166:169], v224 offset:50176
	ds_read_b128 v[170:173], v224 offset:51200
	ds_read_b128 v[178:181], v224 offset:52224
	ds_read_b128 v[202:205], v224 offset:53248
	ds_read_b128 v[206:209], v224 offset:54272
	ds_read_b128 v[226:229], v224 offset:55296
	ds_read_b128 v[230:233], v224 offset:56320
	global_load_lds_dwordx4 v[188:189], off nt
	s_add_i32 m0, s62, 0x2000
	s_add_u32 s62, vcc_lo, 0x80080
	v_lshl_add_u64 v[188:189], v[198:199], 0, s[30:31]
	s_addc_u32 s63, vcc_hi, 0
	s_add_i32 s67, s76, s5
	global_load_lds_dwordx4 v[188:189], off nt
	v_lshl_add_u64 v[188:189], s[62:63], 0, v[96:97]
	s_mov_b32 m0, s67
	s_nop 0
	global_load_lds_dwordx4 v[188:189], off nt
	v_lshl_add_u64 v[188:189], s[62:63], 0, v[182:183]
	s_add_i32 m0, s67, 0x2000
	s_nop 0
	global_load_lds_dwordx4 v[188:189], off nt
	v_lshl_add_u64 v[188:189], v[200:201], 0, s[30:31]
	s_mov_b32 m0, s36
	s_nop 0
	global_load_lds_dwordx4 v[188:189], off
	v_lshl_add_u64 v[188:189], v[234:235], 0, s[30:31]
	s_mov_b32 m0, s37
	s_nop 0
	global_load_lds_dwordx4 v[188:189], off
	s_waitcnt vmcnt(8)
	s_waitcnt lgkmcnt(0)
	s_barrier
	s_setprio 1
	s_waitcnt lgkmcnt(0)
	v_mfma_f32_16x16x32_bf16 v[92:95], v[130:133], v[162:165], v[92:95]
	v_mfma_f32_16x16x32_bf16 v[24:27], v[138:141], v[162:165], v[24:27]
	v_mfma_f32_16x16x32_bf16 v[88:91], v[130:133], v[170:173], v[88:91]
	v_mfma_f32_16x16x32_bf16 v[28:31], v[138:141], v[170:173], v[28:31]
	v_mfma_f32_16x16x32_bf16 v[84:87], v[130:133], v[202:205], v[84:87]
	v_mfma_f32_16x16x32_bf16 v[16:19], v[138:141], v[202:205], v[16:19]
	v_mfma_f32_16x16x32_bf16 v[80:83], v[130:133], v[226:229], v[80:83]
	v_mfma_f32_16x16x32_bf16 v[20:23], v[138:141], v[226:229], v[20:23]
	v_mfma_f32_16x16x32_bf16 v[92:95], v[134:137], v[166:169], v[92:95]
	v_mfma_f32_16x16x32_bf16 v[24:27], v[142:145], v[166:169], v[24:27]
	v_mfma_f32_16x16x32_bf16 v[88:91], v[134:137], v[178:181], v[88:91]
	v_mfma_f32_16x16x32_bf16 v[28:31], v[142:145], v[178:181], v[28:31]
	v_mfma_f32_16x16x32_bf16 v[84:87], v[134:137], v[206:209], v[84:87]
	v_mfma_f32_16x16x32_bf16 v[16:19], v[142:145], v[206:209], v[16:19]
	v_mfma_f32_16x16x32_bf16 v[80:83], v[134:137], v[230:233], v[80:83]
	v_mfma_f32_16x16x32_bf16 v[20:23], v[142:145], v[230:233], v[20:23]
	s_setprio 0
	s_setprio 1
	v_mfma_f32_16x16x32_bf16 v[76:79], v[146:149], v[162:165], v[76:79]
	v_mfma_f32_16x16x32_bf16 v[12:15], v[154:157], v[162:165], v[12:15]
	v_mfma_f32_16x16x32_bf16 v[72:75], v[146:149], v[170:173], v[72:75]
	v_mfma_f32_16x16x32_bf16 v[8:11], v[154:157], v[170:173], v[8:11]
	v_mfma_f32_16x16x32_bf16 v[68:71], v[146:149], v[202:205], v[68:71]
	v_mfma_f32_16x16x32_bf16 v[0:3], v[154:157], v[202:205], v[0:3]
	v_mfma_f32_16x16x32_bf16 v[64:67], v[146:149], v[226:229], v[64:67]
	v_mfma_f32_16x16x32_bf16 v[4:7], v[154:157], v[226:229], v[4:7]
	v_mfma_f32_16x16x32_bf16 v[76:79], v[150:153], v[166:169], v[76:79]
	v_mfma_f32_16x16x32_bf16 v[12:15], v[158:161], v[166:169], v[12:15]
	v_mfma_f32_16x16x32_bf16 v[72:75], v[150:153], v[178:181], v[72:75]
	v_mfma_f32_16x16x32_bf16 v[8:11], v[158:161], v[178:181], v[8:11]
	v_mfma_f32_16x16x32_bf16 v[68:71], v[150:153], v[206:209], v[68:71]
	v_mfma_f32_16x16x32_bf16 v[0:3], v[158:161], v[206:209], v[0:3]
	v_mfma_f32_16x16x32_bf16 v[64:67], v[150:153], v[230:233], v[64:67]
	v_mfma_f32_16x16x32_bf16 v[4:7], v[158:161], v[230:233], v[4:7]
	s_setprio 0
	s_barrier
	s_add_i32 s6, s6, 2
	s_add_u32 s2, s2, 0x100
	s_addc_u32 s3, s3, 0
	s_cmp_gt_u32 s6, 29
	s_mov_b64 s[62:63], s[34:35]
	s_cbranch_scc0 .LBB0_1158
	s_and_b64 vcc, exec, s[24:25]
	s_cbranch_vccz .LBB0_1161
	s_barrier

.LBB0_1333:
	s_add_u32 s38, s42, 0x100
	s_addc_u32 s39, s43, 0
	s_add_i32 s13, 0, 0x10000
	s_cmp_eq_u32 s6, 4
	s_cselect_b32 s47, s25, s39
	s_cselect_b32 s46, s24, s38
	s_cselect_b32 s45, s35, s3
	s_cselect_b32 s44, s34, s2
	s_add_i32 s23, 0, 0x14000
	v_add_u32_e32 v152, s13, v136
	v_add_u32_e32 v168, s23, v136
	ds_read_b128 v[140:143], v152
	ds_read_b128 v[144:147], v152 offset:1024
	ds_read_b128 v[148:151], v152 offset:2048
	ds_read_b128 v[152:155], v152 offset:3072
	ds_read_b128 v[156:159], v168
	ds_read_b128 v[160:163], v168 offset:1024
	ds_read_b128 v[164:167], v168 offset:2048
	ds_read_b128 v[168:171], v168 offset:3072
	v_lshl_add_u64 v[198:199], s[42:43], 0, v[132:133]
	s_add_i32 m0, s5, 0xc000
	ds_read_b128 v[172:175], v139
	ds_read_b128 v[176:179], v139 offset:1024
	ds_read_b128 v[180:183], v139 offset:2048
	ds_read_b128 v[184:187], v139 offset:3072
	ds_read_b128 v[188:191], v139 offset:4096
	ds_read_b128 v[192:195], v139 offset:5120
	ds_read_b128 v[202:205], v139 offset:6144
	ds_read_b128 v[206:209], v139 offset:7168
	global_load_lds_dwordx4 v[198:199], off
	v_lshl_add_u64 v[198:199], s[42:43], 0, v[134:135]
	s_add_i32 m0, s5, 0xe000
	s_nop 0
	global_load_lds_dwordx4 v[198:199], off
	s_waitcnt vmcnt(8)
	s_waitcnt lgkmcnt(0)
	s_barrier
	s_setprio 1
	s_waitcnt lgkmcnt(0)
	v_mfma_f32_16x16x32_bf16 v[126:129], v[140:143], v[172:175], v[126:129]
	v_mfma_f32_16x16x32_bf16 v[122:125], v[148:151], v[172:175], v[122:125]
	v_mfma_f32_16x16x32_bf16 v[118:121], v[140:143], v[180:183], v[118:121]
	v_mfma_f32_16x16x32_bf16 v[114:117], v[148:151], v[180:183], v[114:117]
	v_mfma_f32_16x16x32_bf16 v[106:109], v[140:143], v[188:191], v[106:109]
	v_mfma_f32_16x16x32_bf16 v[98:101], v[148:151], v[188:191], v[98:101]
	v_mfma_f32_16x16x32_bf16 v[88:91], v[140:143], v[202:205], v[88:91]
	v_mfma_f32_16x16x32_bf16 v[80:83], v[148:151], v[202:205], v[80:83]
	v_mfma_f32_16x16x32_bf16 v[126:129], v[144:147], v[176:179], v[126:129]
	v_mfma_f32_16x16x32_bf16 v[122:125], v[152:155], v[176:179], v[122:125]
	v_mfma_f32_16x16x32_bf16 v[118:121], v[144:147], v[184:187], v[118:121]
	v_mfma_f32_16x16x32_bf16 v[114:117], v[152:155], v[184:187], v[114:117]
	v_mfma_f32_16x16x32_bf16 v[106:109], v[144:147], v[192:195], v[106:109]
	v_mfma_f32_16x16x32_bf16 v[98:101], v[152:155], v[192:195], v[98:101]
	v_mfma_f32_16x16x32_bf16 v[88:91], v[144:147], v[206:209], v[88:91]
	v_mfma_f32_16x16x32_bf16 v[80:83], v[152:155], v[206:209], v[80:83]
	s_setprio 0
	s_setprio 1
	v_mfma_f32_16x16x32_bf16 v[110:113], v[156:159], v[172:175], v[110:113]
	v_mfma_f32_16x16x32_bf16 v[102:105], v[164:167], v[172:175], v[102:105]
	v_mfma_f32_16x16x32_bf16 v[92:95], v[156:159], v[180:183], v[92:95]
	v_mfma_f32_16x16x32_bf16 v[84:87], v[164:167], v[180:183], v[84:87]
	v_mfma_f32_16x16x32_bf16 v[76:79], v[156:159], v[188:191], v[76:79]
	v_mfma_f32_16x16x32_bf16 v[72:75], v[164:167], v[188:191], v[72:75]
	v_mfma_f32_16x16x32_bf16 v[68:71], v[156:159], v[202:205], v[68:71]
	v_mfma_f32_16x16x32_bf16 v[64:67], v[164:167], v[202:205], v[64:67]
	v_mfma_f32_16x16x32_bf16 v[110:113], v[160:163], v[176:179], v[110:113]
	v_mfma_f32_16x16x32_bf16 v[102:105], v[168:171], v[176:179], v[102:105]
	v_mfma_f32_16x16x32_bf16 v[92:95], v[160:163], v[184:187], v[92:95]
	v_mfma_f32_16x16x32_bf16 v[84:87], v[168:171], v[184:187], v[84:87]
	v_mfma_f32_16x16x32_bf16 v[76:79], v[160:163], v[192:195], v[76:79]
	v_mfma_f32_16x16x32_bf16 v[72:75], v[168:171], v[192:195], v[72:75]
	v_mfma_f32_16x16x32_bf16 v[68:71], v[160:163], v[206:209], v[68:71]
	v_mfma_f32_16x16x32_bf16 v[64:67], v[168:171], v[206:209], v[64:67]
	s_setprio 0
	s_barrier
	s_add_i32 s13, s13, s4
	v_lshl_add_u64 v[198:199], s[44:45], 0, v[96:97]
	s_mov_b32 m0, s13
	ds_read_b128 v[172:175], v139 offset:16384
	ds_read_b128 v[176:179], v139 offset:17408
	ds_read_b128 v[180:183], v139 offset:18432
	ds_read_b128 v[184:187], v139 offset:19456
	ds_read_b128 v[188:191], v139 offset:20480
	ds_read_b128 v[192:195], v139 offset:21504
	ds_read_b128 v[202:205], v139 offset:22528
	ds_read_b128 v[206:209], v139 offset:23552
	global_load_lds_dwordx4 v[198:199], off nt
	s_add_i32 m0, s13, 0x2000
	s_add_u32 s42, s44, 0x160000
	v_lshl_add_u64 v[200:201], s[44:45], 0, v[130:131]
	s_addc_u32 s43, s45, 0
	s_add_i32 s13, s23, s4
	global_load_lds_dwordx4 v[200:201], off nt
	v_lshl_add_u64 v[214:215], s[42:43], 0, v[96:97]
	s_mov_b32 m0, s13
	v_lshl_add_u64 v[216:217], s[46:47], 0, v[130:131]
	global_load_lds_dwordx4 v[214:215], off nt
	v_lshl_add_u64 v[214:215], s[42:43], 0, v[130:131]
	s_add_i32 m0, s13, 0x2000
	s_nop 0
	global_load_lds_dwordx4 v[214:215], off nt
	v_lshl_add_u64 v[214:215], s[46:47], 0, v[96:97]
	s_mov_b32 m0, s5
	s_nop 0
	global_load_lds_dwordx4 v[214:215], off
	s_mov_b32 m0, s17
	s_nop 0
	global_load_lds_dwordx4 v[216:217], off
	s_waitcnt vmcnt(8)
	s_waitcnt lgkmcnt(0)
	s_barrier
	s_setprio 1
	s_waitcnt lgkmcnt(0)
	v_mfma_f32_16x16x32_bf16 v[60:63], v[140:143], v[172:175], v[60:63]
	v_mfma_f32_16x16x32_bf16 v[56:59], v[148:151], v[172:175], v[56:59]
	v_mfma_f32_16x16x32_bf16 v[52:55], v[140:143], v[180:183], v[52:55]
	v_mfma_f32_16x16x32_bf16 v[48:51], v[148:151], v[180:183], v[48:51]
	v_mfma_f32_16x16x32_bf16 v[36:39], v[140:143], v[188:191], v[36:39]
	v_mfma_f32_16x16x32_bf16 v[32:35], v[148:151], v[188:191], v[32:35]
	v_mfma_f32_16x16x32_bf16 v[20:23], v[140:143], v[202:205], v[20:23]
	v_mfma_f32_16x16x32_bf16 v[16:19], v[148:151], v[202:205], v[16:19]
	v_mfma_f32_16x16x32_bf16 v[60:63], v[144:147], v[176:179], v[60:63]
	v_mfma_f32_16x16x32_bf16 v[56:59], v[152:155], v[176:179], v[56:59]
	v_mfma_f32_16x16x32_bf16 v[52:55], v[144:147], v[184:187], v[52:55]
	v_mfma_f32_16x16x32_bf16 v[48:51], v[152:155], v[184:187], v[48:51]
	v_mfma_f32_16x16x32_bf16 v[36:39], v[144:147], v[192:195], v[36:39]
	v_mfma_f32_16x16x32_bf16 v[32:35], v[152:155], v[192:195], v[32:35]
	v_mfma_f32_16x16x32_bf16 v[20:23], v[144:147], v[206:209], v[20:23]
	v_mfma_f32_16x16x32_bf16 v[16:19], v[152:155], v[206:209], v[16:19]
	s_setprio 0
	s_setprio 1
	v_mfma_f32_16x16x32_bf16 v[44:47], v[156:159], v[172:175], v[44:47]
	v_mfma_f32_16x16x32_bf16 v[40:43], v[164:167], v[172:175], v[40:43]
	v_mfma_f32_16x16x32_bf16 v[28:31], v[156:159], v[180:183], v[28:31]
	v_mfma_f32_16x16x32_bf16 v[24:27], v[164:167], v[180:183], v[24:27]
	v_mfma_f32_16x16x32_bf16 v[12:15], v[156:159], v[188:191], v[12:15]
	v_mfma_f32_16x16x32_bf16 v[8:11], v[164:167], v[188:191], v[8:11]
	v_mfma_f32_16x16x32_bf16 v[4:7], v[156:159], v[202:205], v[4:7]
	v_mfma_f32_16x16x32_bf16 v[0:3], v[164:167], v[202:205], v[0:3]
	v_mfma_f32_16x16x32_bf16 v[44:47], v[160:163], v[176:179], v[44:47]
	v_mfma_f32_16x16x32_bf16 v[40:43], v[168:171], v[176:179], v[40:43]
	v_mfma_f32_16x16x32_bf16 v[28:31], v[160:163], v[184:187], v[28:31]
	v_mfma_f32_16x16x32_bf16 v[24:27], v[168:171], v[184:187], v[24:27]
	v_mfma_f32_16x16x32_bf16 v[12:15], v[160:163], v[192:195], v[12:15]
	v_mfma_f32_16x16x32_bf16 v[8:11], v[168:171], v[192:195], v[8:11]
	v_mfma_f32_16x16x32_bf16 v[4:7], v[160:163], v[206:209], v[4:7]
	v_mfma_f32_16x16x32_bf16 v[0:3], v[168:171], v[206:209], v[0:3]
	s_setprio 0
	s_barrier
	s_add_i32 s13, 0, 0x18000
	s_add_i32 s23, 0, 0x1c000
	v_add_u32_e32 v152, s13, v136
	v_add_u32_e32 v168, s23, v136
	ds_read_b128 v[140:143], v152
	ds_read_b128 v[144:147], v152 offset:1024
	ds_read_b128 v[148:151], v152 offset:2048
	ds_read_b128 v[152:155], v152 offset:3072
	ds_read_b128 v[156:159], v168
	ds_read_b128 v[160:163], v168 offset:1024
	ds_read_b128 v[164:167], v168 offset:2048
	ds_read_b128 v[168:171], v168 offset:3072
	s_add_u32 s42, s46, 0x160000
	s_addc_u32 s43, s47, 0
	s_mov_b32 m0, s18
	v_lshl_add_u64 v[218:219], s[42:43], 0, v[96:97]
	ds_read_b128 v[172:175], v139 offset:32768
	ds_read_b128 v[176:179], v139 offset:33792
	ds_read_b128 v[180:183], v139 offset:34816
	ds_read_b128 v[184:187], v139 offset:35840
	ds_read_b128 v[188:191], v139 offset:36864
	ds_read_b128 v[192:195], v139 offset:37888
	ds_read_b128 v[202:205], v139 offset:38912
	ds_read_b128 v[206:209], v139 offset:39936
	global_load_lds_dwordx4 v[218:219], off
	v_lshl_add_u64 v[218:219], s[42:43], 0, v[130:131]
	s_mov_b32 m0, s19
	s_nop 0
	global_load_lds_dwordx4 v[218:219], off
	s_waitcnt vmcnt(8)
	s_waitcnt lgkmcnt(0)
	s_barrier
	s_setprio 1
	s_waitcnt lgkmcnt(0)
	v_mfma_f32_16x16x32_bf16 v[126:129], v[140:143], v[172:175], v[126:129]
	v_mfma_f32_16x16x32_bf16 v[122:125], v[148:151], v[172:175], v[122:125]
	v_mfma_f32_16x16x32_bf16 v[118:121], v[140:143], v[180:183], v[118:121]
	v_mfma_f32_16x16x32_bf16 v[114:117], v[148:151], v[180:183], v[114:117]
	v_mfma_f32_16x16x32_bf16 v[106:109], v[140:143], v[188:191], v[106:109]
	v_mfma_f32_16x16x32_bf16 v[98:101], v[148:151], v[188:191], v[98:101]
	v_mfma_f32_16x16x32_bf16 v[88:91], v[140:143], v[202:205], v[88:91]
	v_mfma_f32_16x16x32_bf16 v[80:83], v[148:151], v[202:205], v[80:83]
	v_mfma_f32_16x16x32_bf16 v[126:129], v[144:147], v[176:179], v[126:129]
	v_mfma_f32_16x16x32_bf16 v[122:125], v[152:155], v[176:179], v[122:125]
	v_mfma_f32_16x16x32_bf16 v[118:121], v[144:147], v[184:187], v[118:121]
	v_mfma_f32_16x16x32_bf16 v[114:117], v[152:155], v[184:187], v[114:117]
	v_mfma_f32_16x16x32_bf16 v[106:109], v[144:147], v[192:195], v[106:109]
	v_mfma_f32_16x16x32_bf16 v[98:101], v[152:155], v[192:195], v[98:101]
	v_mfma_f32_16x16x32_bf16 v[88:91], v[144:147], v[206:209], v[88:91]
	v_mfma_f32_16x16x32_bf16 v[80:83], v[152:155], v[206:209], v[80:83]
	s_setprio 0
	s_setprio 1
	v_mfma_f32_16x16x32_bf16 v[110:113], v[156:159], v[172:175], v[110:113]
	v_mfma_f32_16x16x32_bf16 v[102:105], v[164:167], v[172:175], v[102:105]
	v_mfma_f32_16x16x32_bf16 v[92:95], v[156:159], v[180:183], v[92:95]
	v_mfma_f32_16x16x32_bf16 v[84:87], v[164:167], v[180:183], v[84:87]
	v_mfma_f32_16x16x32_bf16 v[76:79], v[156:159], v[188:191], v[76:79]
	v_mfma_f32_16x16x32_bf16 v[72:75], v[164:167], v[188:191], v[72:75]
	v_mfma_f32_16x16x32_bf16 v[68:71], v[156:159], v[202:205], v[68:71]
	v_mfma_f32_16x16x32_bf16 v[64:67], v[164:167], v[202:205], v[64:67]
	v_mfma_f32_16x16x32_bf16 v[110:113], v[160:163], v[176:179], v[110:113]
	v_mfma_f32_16x16x32_bf16 v[102:105], v[168:171], v[176:179], v[102:105]
	v_mfma_f32_16x16x32_bf16 v[92:95], v[160:163], v[184:187], v[92:95]
	v_mfma_f32_16x16x32_bf16 v[84:87], v[168:171], v[184:187], v[84:87]
	v_mfma_f32_16x16x32_bf16 v[76:79], v[160:163], v[192:195], v[76:79]
	v_mfma_f32_16x16x32_bf16 v[72:75], v[168:171], v[192:195], v[72:75]
	v_mfma_f32_16x16x32_bf16 v[68:71], v[160:163], v[206:209], v[68:71]
	v_mfma_f32_16x16x32_bf16 v[64:67], v[168:171], v[206:209], v[64:67]
	s_setprio 0
	s_barrier
	s_add_i32 s13, s13, s4
	v_lshl_add_u64 v[198:199], v[198:199], 0, s[30:31]
	s_mov_b32 m0, s13
	ds_read_b128 v[172:175], v139 offset:49152
	ds_read_b128 v[176:179], v139 offset:50176
	ds_read_b128 v[180:183], v139 offset:51200
	ds_read_b128 v[184:187], v139 offset:52224
	ds_read_b128 v[188:191], v139 offset:53248
	ds_read_b128 v[192:195], v139 offset:54272
	ds_read_b128 v[202:205], v139 offset:55296
	ds_read_b128 v[206:209], v139 offset:56320
	global_load_lds_dwordx4 v[198:199], off nt
	s_add_i32 m0, s13, 0x2000
	s_add_u32 s42, s44, 0x160080
	v_lshl_add_u64 v[198:199], v[200:201], 0, s[30:31]
	s_addc_u32 s43, s45, 0
	s_add_i32 s13, s23, s4
	global_load_lds_dwordx4 v[198:199], off nt
	v_lshl_add_u64 v[198:199], s[42:43], 0, v[96:97]
	s_mov_b32 m0, s13
	s_nop 0
	global_load_lds_dwordx4 v[198:199], off nt
	v_lshl_add_u64 v[198:199], s[42:43], 0, v[130:131]
	s_add_i32 m0, s13, 0x2000
	s_nop 0
	global_load_lds_dwordx4 v[198:199], off nt
	v_lshl_add_u64 v[198:199], v[214:215], 0, s[30:31]
	s_mov_b32 m0, s37
	s_nop 0
	global_load_lds_dwordx4 v[198:199], off
	v_lshl_add_u64 v[198:199], v[216:217], 0, s[30:31]
	s_mov_b32 m0, s40
	s_nop 0
	global_load_lds_dwordx4 v[198:199], off
	s_waitcnt vmcnt(8)
	s_waitcnt lgkmcnt(0)
	s_barrier
	s_setprio 1
	s_waitcnt lgkmcnt(0)
	v_mfma_f32_16x16x32_bf16 v[60:63], v[140:143], v[172:175], v[60:63]
	v_mfma_f32_16x16x32_bf16 v[56:59], v[148:151], v[172:175], v[56:59]
	v_mfma_f32_16x16x32_bf16 v[52:55], v[140:143], v[180:183], v[52:55]
	v_mfma_f32_16x16x32_bf16 v[48:51], v[148:151], v[180:183], v[48:51]
	v_mfma_f32_16x16x32_bf16 v[36:39], v[140:143], v[188:191], v[36:39]
	v_mfma_f32_16x16x32_bf16 v[32:35], v[148:151], v[188:191], v[32:35]
	v_mfma_f32_16x16x32_bf16 v[20:23], v[140:143], v[202:205], v[20:23]
	v_mfma_f32_16x16x32_bf16 v[16:19], v[148:151], v[202:205], v[16:19]
	v_mfma_f32_16x16x32_bf16 v[60:63], v[144:147], v[176:179], v[60:63]
	v_mfma_f32_16x16x32_bf16 v[56:59], v[152:155], v[176:179], v[56:59]
	v_mfma_f32_16x16x32_bf16 v[52:55], v[144:147], v[184:187], v[52:55]
	v_mfma_f32_16x16x32_bf16 v[48:51], v[152:155], v[184:187], v[48:51]
	v_mfma_f32_16x16x32_bf16 v[36:39], v[144:147], v[192:195], v[36:39]
	v_mfma_f32_16x16x32_bf16 v[32:35], v[152:155], v[192:195], v[32:35]
	v_mfma_f32_16x16x32_bf16 v[20:23], v[144:147], v[206:209], v[20:23]
	v_mfma_f32_16x16x32_bf16 v[16:19], v[152:155], v[206:209], v[16:19]
	s_setprio 0
	s_setprio 1
	v_mfma_f32_16x16x32_bf16 v[44:47], v[156:159], v[172:175], v[44:47]
	v_mfma_f32_16x16x32_bf16 v[40:43], v[164:167], v[172:175], v[40:43]
	v_mfma_f32_16x16x32_bf16 v[28:31], v[156:159], v[180:183], v[28:31]
	v_mfma_f32_16x16x32_bf16 v[24:27], v[164:167], v[180:183], v[24:27]
	v_mfma_f32_16x16x32_bf16 v[12:15], v[156:159], v[188:191], v[12:15]
	v_mfma_f32_16x16x32_bf16 v[8:11], v[164:167], v[188:191], v[8:11]
	v_mfma_f32_16x16x32_bf16 v[4:7], v[156:159], v[202:205], v[4:7]
	v_mfma_f32_16x16x32_bf16 v[0:3], v[164:167], v[202:205], v[0:3]
	v_mfma_f32_16x16x32_bf16 v[44:47], v[160:163], v[176:179], v[44:47]
	v_mfma_f32_16x16x32_bf16 v[40:43], v[168:171], v[176:179], v[40:43]
	v_mfma_f32_16x16x32_bf16 v[28:31], v[160:163], v[184:187], v[28:31]
	v_mfma_f32_16x16x32_bf16 v[24:27], v[168:171], v[184:187], v[24:27]
	v_mfma_f32_16x16x32_bf16 v[12:15], v[160:163], v[192:195], v[12:15]
	v_mfma_f32_16x16x32_bf16 v[8:11], v[168:171], v[192:195], v[8:11]
	v_mfma_f32_16x16x32_bf16 v[4:7], v[160:163], v[206:209], v[4:7]
	v_mfma_f32_16x16x32_bf16 v[0:3], v[168:171], v[206:209], v[0:3]
	s_setprio 0
	s_barrier
	s_add_i32 s6, s6, 2
	s_add_u32 s2, s2, 0x100
	s_addc_u32 s3, s3, 0
	s_cmp_gt_u32 s6, 5
	s_mov_b64 s[42:43], s[38:39]
	s_cbranch_scc0 .LBB0_1333
	s_and_b64 vcc, exec, s[14:15]
	s_cbranch_vccz .LBB0_1336
	s_barrier

.LBB0_1357:
	s_add_u32 s3, s14, s34
	s_addc_u32 s6, s15, s35
	s_add_u32 s3, s3, 0x100
	s_addc_u32 s6, s6, 0
	s_add_u32 s42, s57, s34
	s_addc_u32 s43, s58, s35
	s_add_i32 s59, 0, 0x10000
	s_cmpk_eq_i32 s34, 0x2b00
	s_cselect_b32 s45, s23, s6
	s_cselect_b32 s44, s22, s3
	v_add_u32_e32 v146, s59, v144
	s_cselect_b32 s43, s25, s43
	s_cselect_b32 s42, s24, s42
	s_add_i32 s3, 0, 0x14000
	ds_read_b128 v[154:157], v146
	ds_read_b128 v[158:161], v146 offset:1024
	ds_read_b128 v[162:165], v146 offset:2048
	ds_read_b128 v[166:169], v146 offset:3072
	v_add_u32_e32 v146, s3, v144
	ds_read_b128 v[174:177], v146
	ds_read_b128 v[178:181], v146 offset:1024
	ds_read_b128 v[182:185], v146 offset:2048
	ds_read_b128 v[186:189], v146 offset:3072
	v_lshl_add_u64 v[146:147], v[140:141], 0, s[34:35]
	s_add_i32 m0, s17, 0xc000
	ds_read_b128 v[190:193], v145
	ds_read_b128 v[202:205], v145 offset:1024
	ds_read_b128 v[206:209], v145 offset:2048
	ds_read_b128 v[214:217], v145 offset:3072
	ds_read_b128 v[218:221], v145 offset:4096
	ds_read_b128 v[222:225], v145 offset:5120
	ds_read_b128 v[226:229], v145 offset:6144
	ds_read_b128 v[230:233], v145 offset:7168
	global_load_lds_dwordx4 v[146:147], off
	v_lshl_add_u64 v[146:147], v[142:143], 0, s[34:35]
	s_add_i32 m0, s17, 0xe000
	s_nop 0
	global_load_lds_dwordx4 v[146:147], off
	s_waitcnt vmcnt(8)
	s_waitcnt lgkmcnt(0)
	s_barrier
	s_setprio 1
	s_waitcnt lgkmcnt(0)
	v_mfma_f32_16x16x32_bf16 v[110:113], v[154:157], v[190:193], v[110:113]
	v_mfma_f32_16x16x32_bf16 v[106:109], v[162:165], v[190:193], v[106:109]
	v_mfma_f32_16x16x32_bf16 v[118:121], v[154:157], v[206:209], v[118:121]
	v_mfma_f32_16x16x32_bf16 v[114:117], v[162:165], v[206:209], v[114:117]
	v_mfma_f32_16x16x32_bf16 v[126:129], v[154:157], v[218:221], v[126:129]
	v_mfma_f32_16x16x32_bf16 v[122:125], v[162:165], v[218:221], v[122:125]
	v_mfma_f32_16x16x32_bf16 v[92:95], v[154:157], v[226:229], v[92:95]
	v_mfma_f32_16x16x32_bf16 v[88:91], v[162:165], v[226:229], v[88:91]
	v_mfma_f32_16x16x32_bf16 v[110:113], v[158:161], v[202:205], v[110:113]
	v_mfma_f32_16x16x32_bf16 v[106:109], v[166:169], v[202:205], v[106:109]
	v_mfma_f32_16x16x32_bf16 v[118:121], v[158:161], v[214:217], v[118:121]
	v_mfma_f32_16x16x32_bf16 v[114:117], v[166:169], v[214:217], v[114:117]
	v_mfma_f32_16x16x32_bf16 v[126:129], v[158:161], v[222:225], v[126:129]
	v_mfma_f32_16x16x32_bf16 v[122:125], v[166:169], v[222:225], v[122:125]
	v_mfma_f32_16x16x32_bf16 v[92:95], v[158:161], v[230:233], v[92:95]
	v_mfma_f32_16x16x32_bf16 v[88:91], v[166:169], v[230:233], v[88:91]
	s_setprio 0
	s_setprio 1
	v_mfma_f32_16x16x32_bf16 v[4:7], v[174:177], v[190:193], v[4:7]
	v_mfma_f32_16x16x32_bf16 v[0:3], v[182:185], v[190:193], v[0:3]
	v_mfma_f32_16x16x32_bf16 v[12:15], v[174:177], v[206:209], v[12:15]
	v_mfma_f32_16x16x32_bf16 v[8:11], v[182:185], v[206:209], v[8:11]
	v_mfma_f32_16x16x32_bf16 v[24:27], v[174:177], v[218:221], v[24:27]
	v_mfma_f32_16x16x32_bf16 v[20:23], v[182:185], v[218:221], v[20:23]
	v_mfma_f32_16x16x32_bf16 v[40:43], v[174:177], v[226:229], v[40:43]
	v_mfma_f32_16x16x32_bf16 v[36:39], v[182:185], v[226:229], v[36:39]
	v_mfma_f32_16x16x32_bf16 v[4:7], v[178:181], v[202:205], v[4:7]
	v_mfma_f32_16x16x32_bf16 v[0:3], v[186:189], v[202:205], v[0:3]
	v_mfma_f32_16x16x32_bf16 v[12:15], v[178:181], v[214:217], v[12:15]
	v_mfma_f32_16x16x32_bf16 v[8:11], v[186:189], v[214:217], v[8:11]
	v_mfma_f32_16x16x32_bf16 v[24:27], v[178:181], v[222:225], v[24:27]
	v_mfma_f32_16x16x32_bf16 v[20:23], v[186:189], v[222:225], v[20:23]
	v_mfma_f32_16x16x32_bf16 v[40:43], v[178:181], v[230:233], v[40:43]
	v_mfma_f32_16x16x32_bf16 v[36:39], v[186:189], v[230:233], v[36:39]
	s_setprio 0
	s_barrier
	s_add_i32 s6, s59, s5
	v_lshl_add_u64 v[146:147], s[42:43], 0, v[96:97]
	s_mov_b32 m0, s6
	ds_read_b128 v[190:193], v145 offset:16384
	ds_read_b128 v[202:205], v145 offset:17408
	ds_read_b128 v[206:209], v145 offset:18432
	ds_read_b128 v[214:217], v145 offset:19456
	ds_read_b128 v[218:221], v145 offset:20480
	ds_read_b128 v[222:225], v145 offset:21504
	ds_read_b128 v[226:229], v145 offset:22528
	ds_read_b128 v[230:233], v145 offset:23552
	global_load_lds_dwordx4 v[146:147], off nt
	s_add_i32 m0, s6, 0x2000
	s_add_u32 s60, s42, 0x160000
	v_lshl_add_u64 v[150:151], s[42:43], 0, v[130:131]
	s_addc_u32 s61, s43, 0
	s_add_i32 s3, s3, s5
	global_load_lds_dwordx4 v[150:151], off nt
	v_lshl_add_u64 v[170:171], s[60:61], 0, v[96:97]
	s_mov_b32 m0, s3
	v_lshl_add_u64 v[194:195], s[44:45], 0, v[132:133]
	global_load_lds_dwordx4 v[170:171], off nt
	v_lshl_add_u64 v[170:171], s[60:61], 0, v[130:131]
	s_add_i32 m0, s3, 0x2000
	s_nop 0
	global_load_lds_dwordx4 v[170:171], off nt
	v_lshl_add_u64 v[170:171], s[44:45], 0, v[134:135]
	s_mov_b32 m0, s17
	s_nop 0
	global_load_lds_dwordx4 v[170:171], off
	s_mov_b32 m0, s18
	s_nop 0
	global_load_lds_dwordx4 v[194:195], off
	s_waitcnt vmcnt(8)
	s_waitcnt lgkmcnt(0)
	s_barrier
	s_setprio 1
	s_waitcnt lgkmcnt(0)
	v_mfma_f32_16x16x32_bf16 v[102:105], v[154:157], v[190:193], v[102:105]
	v_mfma_f32_16x16x32_bf16 v[98:101], v[162:165], v[190:193], v[98:101]
	v_mfma_f32_16x16x32_bf16 v[84:87], v[154:157], v[206:209], v[84:87]
	v_mfma_f32_16x16x32_bf16 v[80:83], v[162:165], v[206:209], v[80:83]
	v_mfma_f32_16x16x32_bf16 v[68:71], v[154:157], v[218:221], v[68:71]
	v_mfma_f32_16x16x32_bf16 v[64:67], v[162:165], v[218:221], v[64:67]
	v_mfma_f32_16x16x32_bf16 v[44:47], v[154:157], v[226:229], v[44:47]
	v_mfma_f32_16x16x32_bf16 v[32:35], v[162:165], v[226:229], v[32:35]
	v_mfma_f32_16x16x32_bf16 v[102:105], v[158:161], v[202:205], v[102:105]
	v_mfma_f32_16x16x32_bf16 v[98:101], v[166:169], v[202:205], v[98:101]
	v_mfma_f32_16x16x32_bf16 v[84:87], v[158:161], v[214:217], v[84:87]
	v_mfma_f32_16x16x32_bf16 v[80:83], v[166:169], v[214:217], v[80:83]
	v_mfma_f32_16x16x32_bf16 v[68:71], v[158:161], v[222:225], v[68:71]
	v_mfma_f32_16x16x32_bf16 v[64:67], v[166:169], v[222:225], v[64:67]
	v_mfma_f32_16x16x32_bf16 v[44:47], v[158:161], v[230:233], v[44:47]
	v_mfma_f32_16x16x32_bf16 v[32:35], v[166:169], v[230:233], v[32:35]
	s_setprio 0
	s_setprio 1
	v_mfma_f32_16x16x32_bf16 v[60:63], v[174:177], v[190:193], v[60:63]
	v_mfma_f32_16x16x32_bf16 v[56:59], v[182:185], v[190:193], v[56:59]
	v_mfma_f32_16x16x32_bf16 v[76:79], v[174:177], v[206:209], v[76:79]
	v_mfma_f32_16x16x32_bf16 v[72:75], v[182:185], v[206:209], v[72:75]
	v_mfma_f32_16x16x32_bf16 v[52:55], v[174:177], v[218:221], v[52:55]
	v_mfma_f32_16x16x32_bf16 v[48:51], v[182:185], v[218:221], v[48:51]
	v_mfma_f32_16x16x32_bf16 v[28:31], v[174:177], v[226:229], v[28:31]
	v_mfma_f32_16x16x32_bf16 v[16:19], v[182:185], v[226:229], v[16:19]
	v_mfma_f32_16x16x32_bf16 v[60:63], v[178:181], v[202:205], v[60:63]
	v_mfma_f32_16x16x32_bf16 v[56:59], v[186:189], v[202:205], v[56:59]
	v_mfma_f32_16x16x32_bf16 v[76:79], v[178:181], v[214:217], v[76:79]
	v_mfma_f32_16x16x32_bf16 v[72:75], v[186:189], v[214:217], v[72:75]
	v_mfma_f32_16x16x32_bf16 v[52:55], v[178:181], v[222:225], v[52:55]
	v_mfma_f32_16x16x32_bf16 v[48:51], v[186:189], v[222:225], v[48:51]
	v_mfma_f32_16x16x32_bf16 v[28:31], v[178:181], v[230:233], v[28:31]
	v_mfma_f32_16x16x32_bf16 v[16:19], v[186:189], v[230:233], v[16:19]
	s_setprio 0
	s_barrier
	s_add_i32 s3, 0, 0x18000
	v_add_u32_e32 v149, s3, v144
	s_add_i32 s6, 0, 0x1c000
	ds_read_b128 v[154:157], v149
	ds_read_b128 v[158:161], v149 offset:1024
	ds_read_b128 v[162:165], v149 offset:2048
	ds_read_b128 v[166:169], v149 offset:3072
	v_add_u32_e32 v149, s6, v144
	ds_read_b128 v[174:177], v149
	ds_read_b128 v[178:181], v149 offset:1024
	ds_read_b128 v[182:185], v149 offset:2048
	ds_read_b128 v[186:189], v149 offset:3072
	s_add_u32 s44, s44, 0x160000
	s_addc_u32 s45, s45, 0
	s_mov_b32 m0, s19
	v_lshl_add_u64 v[198:199], s[44:45], 0, v[134:135]
	ds_read_b128 v[190:193], v145 offset:32768
	ds_read_b128 v[202:205], v145 offset:33792
	ds_read_b128 v[206:209], v145 offset:34816
	ds_read_b128 v[214:217], v145 offset:35840
	ds_read_b128 v[218:221], v145 offset:36864
	ds_read_b128 v[222:225], v145 offset:37888
	ds_read_b128 v[226:229], v145 offset:38912
	ds_read_b128 v[230:233], v145 offset:39936
	global_load_lds_dwordx4 v[198:199], off
	v_lshl_add_u64 v[198:199], s[44:45], 0, v[132:133]
	s_mov_b32 m0, s20
	s_nop 0
	global_load_lds_dwordx4 v[198:199], off
	s_waitcnt vmcnt(8)
	s_waitcnt lgkmcnt(0)
	s_barrier
	s_setprio 1
	s_waitcnt lgkmcnt(0)
	v_mfma_f32_16x16x32_bf16 v[110:113], v[154:157], v[190:193], v[110:113]
	v_mfma_f32_16x16x32_bf16 v[106:109], v[162:165], v[190:193], v[106:109]
	v_mfma_f32_16x16x32_bf16 v[118:121], v[154:157], v[206:209], v[118:121]
	v_mfma_f32_16x16x32_bf16 v[114:117], v[162:165], v[206:209], v[114:117]
	v_mfma_f32_16x16x32_bf16 v[126:129], v[154:157], v[218:221], v[126:129]
	v_mfma_f32_16x16x32_bf16 v[122:125], v[162:165], v[218:221], v[122:125]
	v_mfma_f32_16x16x32_bf16 v[92:95], v[154:157], v[226:229], v[92:95]
	v_mfma_f32_16x16x32_bf16 v[88:91], v[162:165], v[226:229], v[88:91]
	v_mfma_f32_16x16x32_bf16 v[110:113], v[158:161], v[202:205], v[110:113]
	v_mfma_f32_16x16x32_bf16 v[106:109], v[166:169], v[202:205], v[106:109]
	v_mfma_f32_16x16x32_bf16 v[118:121], v[158:161], v[214:217], v[118:121]
	v_mfma_f32_16x16x32_bf16 v[114:117], v[166:169], v[214:217], v[114:117]
	v_mfma_f32_16x16x32_bf16 v[126:129], v[158:161], v[222:225], v[126:129]
	v_mfma_f32_16x16x32_bf16 v[122:125], v[166:169], v[222:225], v[122:125]
	v_mfma_f32_16x16x32_bf16 v[92:95], v[158:161], v[230:233], v[92:95]
	v_mfma_f32_16x16x32_bf16 v[88:91], v[166:169], v[230:233], v[88:91]
	s_setprio 0
	s_setprio 1
	v_mfma_f32_16x16x32_bf16 v[4:7], v[174:177], v[190:193], v[4:7]
	v_mfma_f32_16x16x32_bf16 v[0:3], v[182:185], v[190:193], v[0:3]
	v_mfma_f32_16x16x32_bf16 v[12:15], v[174:177], v[206:209], v[12:15]
	v_mfma_f32_16x16x32_bf16 v[8:11], v[182:185], v[206:209], v[8:11]
	v_mfma_f32_16x16x32_bf16 v[24:27], v[174:177], v[218:221], v[24:27]
	v_mfma_f32_16x16x32_bf16 v[20:23], v[182:185], v[218:221], v[20:23]
	v_mfma_f32_16x16x32_bf16 v[40:43], v[174:177], v[226:229], v[40:43]
	v_mfma_f32_16x16x32_bf16 v[36:39], v[182:185], v[226:229], v[36:39]
	v_mfma_f32_16x16x32_bf16 v[4:7], v[178:181], v[202:205], v[4:7]
	v_mfma_f32_16x16x32_bf16 v[0:3], v[186:189], v[202:205], v[0:3]
	v_mfma_f32_16x16x32_bf16 v[12:15], v[178:181], v[214:217], v[12:15]
	v_mfma_f32_16x16x32_bf16 v[8:11], v[186:189], v[214:217], v[8:11]
	v_mfma_f32_16x16x32_bf16 v[24:27], v[178:181], v[222:225], v[24:27]
	v_mfma_f32_16x16x32_bf16 v[20:23], v[186:189], v[222:225], v[20:23]
	v_mfma_f32_16x16x32_bf16 v[40:43], v[178:181], v[230:233], v[40:43]
	v_mfma_f32_16x16x32_bf16 v[36:39], v[186:189], v[230:233], v[36:39]
	s_setprio 0
	s_barrier
	s_add_i32 s3, s3, s5
	v_lshl_add_u64 v[146:147], v[146:147], 0, s[30:31]
	s_mov_b32 m0, s3
	ds_read_b128 v[190:193], v145 offset:49152
	ds_read_b128 v[202:205], v145 offset:50176
	ds_read_b128 v[206:209], v145 offset:51200
	ds_read_b128 v[214:217], v145 offset:52224
	ds_read_b128 v[218:221], v145 offset:53248
	ds_read_b128 v[222:225], v145 offset:54272
	ds_read_b128 v[226:229], v145 offset:55296
	ds_read_b128 v[230:233], v145 offset:56320
	global_load_lds_dwordx4 v[146:147], off nt
	s_add_i32 m0, s3, 0x2000
	s_add_u32 s42, s42, 0x160080
	v_lshl_add_u64 v[146:147], v[150:151], 0, s[30:31]
	s_addc_u32 s43, s43, 0
	s_add_i32 s3, s6, s5
	global_load_lds_dwordx4 v[146:147], off nt
	v_lshl_add_u64 v[146:147], s[42:43], 0, v[96:97]
	s_mov_b32 m0, s3
	s_nop 0
	global_load_lds_dwordx4 v[146:147], off nt
	v_lshl_add_u64 v[146:147], s[42:43], 0, v[130:131]
	s_add_i32 m0, s3, 0x2000
	s_nop 0
	global_load_lds_dwordx4 v[146:147], off nt
	v_lshl_add_u64 v[146:147], v[170:171], 0, s[30:31]
	s_mov_b32 m0, s37
	s_nop 0
	global_load_lds_dwordx4 v[146:147], off
	v_lshl_add_u64 v[146:147], v[194:195], 0, s[30:31]
	s_mov_b32 m0, s52
	s_nop 0
	global_load_lds_dwordx4 v[146:147], off
	s_waitcnt vmcnt(8)
	s_waitcnt lgkmcnt(0)
	s_barrier
	s_setprio 1
	s_waitcnt lgkmcnt(0)
	v_mfma_f32_16x16x32_bf16 v[102:105], v[154:157], v[190:193], v[102:105]
	v_mfma_f32_16x16x32_bf16 v[98:101], v[162:165], v[190:193], v[98:101]
	v_mfma_f32_16x16x32_bf16 v[84:87], v[154:157], v[206:209], v[84:87]
	v_mfma_f32_16x16x32_bf16 v[80:83], v[162:165], v[206:209], v[80:83]
	v_mfma_f32_16x16x32_bf16 v[68:71], v[154:157], v[218:221], v[68:71]
	v_mfma_f32_16x16x32_bf16 v[64:67], v[162:165], v[218:221], v[64:67]
	v_mfma_f32_16x16x32_bf16 v[44:47], v[154:157], v[226:229], v[44:47]
	v_mfma_f32_16x16x32_bf16 v[32:35], v[162:165], v[226:229], v[32:35]
	v_mfma_f32_16x16x32_bf16 v[102:105], v[158:161], v[202:205], v[102:105]
	v_mfma_f32_16x16x32_bf16 v[98:101], v[166:169], v[202:205], v[98:101]
	v_mfma_f32_16x16x32_bf16 v[84:87], v[158:161], v[214:217], v[84:87]
	v_mfma_f32_16x16x32_bf16 v[80:83], v[166:169], v[214:217], v[80:83]
	v_mfma_f32_16x16x32_bf16 v[68:71], v[158:161], v[222:225], v[68:71]
	v_mfma_f32_16x16x32_bf16 v[64:67], v[166:169], v[222:225], v[64:67]
	v_mfma_f32_16x16x32_bf16 v[44:47], v[158:161], v[230:233], v[44:47]
	v_mfma_f32_16x16x32_bf16 v[32:35], v[166:169], v[230:233], v[32:35]
	s_setprio 0
	s_setprio 1
	v_mfma_f32_16x16x32_bf16 v[60:63], v[174:177], v[190:193], v[60:63]
	v_mfma_f32_16x16x32_bf16 v[56:59], v[182:185], v[190:193], v[56:59]
	v_mfma_f32_16x16x32_bf16 v[76:79], v[174:177], v[206:209], v[76:79]
	v_mfma_f32_16x16x32_bf16 v[72:75], v[182:185], v[206:209], v[72:75]
	v_mfma_f32_16x16x32_bf16 v[52:55], v[174:177], v[218:221], v[52:55]
	v_mfma_f32_16x16x32_bf16 v[48:51], v[182:185], v[218:221], v[48:51]
	v_mfma_f32_16x16x32_bf16 v[28:31], v[174:177], v[226:229], v[28:31]
	v_mfma_f32_16x16x32_bf16 v[16:19], v[182:185], v[226:229], v[16:19]
	v_mfma_f32_16x16x32_bf16 v[60:63], v[178:181], v[202:205], v[60:63]
	v_mfma_f32_16x16x32_bf16 v[56:59], v[186:189], v[202:205], v[56:59]
	v_mfma_f32_16x16x32_bf16 v[76:79], v[178:181], v[214:217], v[76:79]
	v_mfma_f32_16x16x32_bf16 v[72:75], v[186:189], v[214:217], v[72:75]
	v_mfma_f32_16x16x32_bf16 v[52:55], v[178:181], v[222:225], v[52:55]
	v_mfma_f32_16x16x32_bf16 v[48:51], v[186:189], v[222:225], v[48:51]
	v_mfma_f32_16x16x32_bf16 v[28:31], v[178:181], v[230:233], v[28:31]
	v_mfma_f32_16x16x32_bf16 v[16:19], v[186:189], v[230:233], v[16:19]
	s_setprio 0
	s_barrier
	s_add_i32 s2, s2, 2
	s_add_u32 s34, s34, 0x100
	s_addc_u32 s35, s35, 0
	s_cmpk_gt_u32 s2, 0x55
	s_cbranch_scc0 .LBB0_1357
	s_and_b64 vcc, exec, s[12:13]
	s_cbranch_vccz .LBB0_1360
	s_barrier

.LBB0_1413:
	s_add_u32 s24, s22, 0x100
	s_addc_u32 s25, s23, 0
	s_add_i32 s45, 0, 0x10000
	s_cmpk_eq_i32 s6, 0x54
	s_cselect_b32 s39, s13, s25
	s_cselect_b32 s38, s12, s24
	s_cselect_b32 s35, s15, s3
	s_cselect_b32 s34, s14, s2
	s_add_i32 s46, 0, 0x14000
	v_add_u32_e32 v142, s45, v155
	v_add_u32_e32 v152, s46, v155
	ds_read_b128 v[130:133], v142
	ds_read_b128 v[134:137], v142 offset:1024
	ds_read_b128 v[138:141], v142 offset:2048
	ds_read_b128 v[142:145], v142 offset:3072
	ds_read_b128 v[158:161], v152
	ds_read_b128 v[162:165], v152 offset:1024
	ds_read_b128 v[166:169], v152 offset:2048
	ds_read_b128 v[170:173], v152 offset:3072
	v_lshl_add_u64 v[152:153], s[22:23], 0, v[148:149]
	s_add_i32 m0, s5, 0xc000
	ds_read_b128 v[174:177], v157
	ds_read_b128 v[178:181], v157 offset:1024
	ds_read_b128 v[182:185], v157 offset:2048
	ds_read_b128 v[186:189], v157 offset:3072
	ds_read_b128 v[190:193], v157 offset:4096
	ds_read_b128 v[202:205], v157 offset:5120
	ds_read_b128 v[206:209], v157 offset:6144
	ds_read_b128 v[214:217], v157 offset:7168
	global_load_lds_dwordx4 v[152:153], off
	v_lshl_add_u64 v[152:153], s[22:23], 0, v[150:151]
	s_add_i32 m0, s5, 0xe000
	s_nop 0
	global_load_lds_dwordx4 v[152:153], off
	s_waitcnt vmcnt(8)
	s_waitcnt lgkmcnt(0)
	s_barrier
	s_setprio 1
	s_waitcnt lgkmcnt(0)
	v_mfma_f32_16x16x32_bf16 v[126:129], v[130:133], v[174:177], v[126:129]
	v_mfma_f32_16x16x32_bf16 v[122:125], v[138:141], v[174:177], v[122:125]
	v_mfma_f32_16x16x32_bf16 v[114:117], v[130:133], v[182:185], v[114:117]
	v_mfma_f32_16x16x32_bf16 v[110:113], v[138:141], v[182:185], v[110:113]
	v_mfma_f32_16x16x32_bf16 v[98:101], v[130:133], v[190:193], v[98:101]
	v_mfma_f32_16x16x32_bf16 v[92:95], v[138:141], v[190:193], v[92:95]
	v_mfma_f32_16x16x32_bf16 v[80:83], v[130:133], v[206:209], v[80:83]
	v_mfma_f32_16x16x32_bf16 v[76:79], v[138:141], v[206:209], v[76:79]
	v_mfma_f32_16x16x32_bf16 v[126:129], v[134:137], v[178:181], v[126:129]
	v_mfma_f32_16x16x32_bf16 v[122:125], v[142:145], v[178:181], v[122:125]
	v_mfma_f32_16x16x32_bf16 v[114:117], v[134:137], v[186:189], v[114:117]
	v_mfma_f32_16x16x32_bf16 v[110:113], v[142:145], v[186:189], v[110:113]
	v_mfma_f32_16x16x32_bf16 v[98:101], v[134:137], v[202:205], v[98:101]
	v_mfma_f32_16x16x32_bf16 v[92:95], v[142:145], v[202:205], v[92:95]
	v_mfma_f32_16x16x32_bf16 v[80:83], v[134:137], v[214:217], v[80:83]
	v_mfma_f32_16x16x32_bf16 v[76:79], v[142:145], v[214:217], v[76:79]
	s_setprio 0
	s_setprio 1
	v_mfma_f32_16x16x32_bf16 v[118:121], v[158:161], v[174:177], v[118:121]
	v_mfma_f32_16x16x32_bf16 v[106:109], v[166:169], v[174:177], v[106:109]
	v_mfma_f32_16x16x32_bf16 v[102:105], v[158:161], v[182:185], v[102:105]
	v_mfma_f32_16x16x32_bf16 v[88:91], v[166:169], v[182:185], v[88:91]
	v_mfma_f32_16x16x32_bf16 v[84:87], v[158:161], v[190:193], v[84:87]
	v_mfma_f32_16x16x32_bf16 v[72:75], v[166:169], v[190:193], v[72:75]
	v_mfma_f32_16x16x32_bf16 v[68:71], v[158:161], v[206:209], v[68:71]
	v_mfma_f32_16x16x32_bf16 v[64:67], v[166:169], v[206:209], v[64:67]
	v_mfma_f32_16x16x32_bf16 v[118:121], v[162:165], v[178:181], v[118:121]
	v_mfma_f32_16x16x32_bf16 v[106:109], v[170:173], v[178:181], v[106:109]
	v_mfma_f32_16x16x32_bf16 v[102:105], v[162:165], v[186:189], v[102:105]
	v_mfma_f32_16x16x32_bf16 v[88:91], v[170:173], v[186:189], v[88:91]
	v_mfma_f32_16x16x32_bf16 v[84:87], v[162:165], v[202:205], v[84:87]
	v_mfma_f32_16x16x32_bf16 v[72:75], v[170:173], v[202:205], v[72:75]
	v_mfma_f32_16x16x32_bf16 v[68:71], v[162:165], v[214:217], v[68:71]
	v_mfma_f32_16x16x32_bf16 v[64:67], v[170:173], v[214:217], v[64:67]
	s_setprio 0
	s_barrier
	s_add_i32 s22, s45, s4
	v_lshl_add_u64 v[152:153], s[34:35], 0, v[96:97]
	s_mov_b32 m0, s22
	ds_read_b128 v[174:177], v157 offset:16384
	ds_read_b128 v[178:181], v157 offset:17408
	ds_read_b128 v[182:185], v157 offset:18432
	ds_read_b128 v[186:189], v157 offset:19456
	ds_read_b128 v[190:193], v157 offset:20480
	ds_read_b128 v[202:205], v157 offset:21504
	ds_read_b128 v[206:209], v157 offset:22528
	ds_read_b128 v[214:217], v157 offset:23552
	global_load_lds_dwordx4 v[152:153], off nt
	s_add_i32 m0, s22, 0x2000
	s_add_u32 s22, s34, 0x160000
	v_lshl_add_u64 v[194:195], s[34:35], 0, v[146:147]
	s_addc_u32 s23, s35, 0
	s_add_i32 s45, s46, s4
	global_load_lds_dwordx4 v[194:195], off nt
	v_lshl_add_u64 v[198:199], s[22:23], 0, v[96:97]
	s_mov_b32 m0, s45
	v_lshl_add_u64 v[200:201], s[38:39], 0, v[146:147]
	global_load_lds_dwordx4 v[198:199], off nt
	v_lshl_add_u64 v[198:199], s[22:23], 0, v[146:147]
	s_add_i32 m0, s45, 0x2000
	s_nop 0
	global_load_lds_dwordx4 v[198:199], off nt
	v_lshl_add_u64 v[198:199], s[38:39], 0, v[96:97]
	s_mov_b32 m0, s5
	s_nop 0
	global_load_lds_dwordx4 v[198:199], off
	s_mov_b32 m0, s17
	s_nop 0
	global_load_lds_dwordx4 v[200:201], off
	s_waitcnt vmcnt(8)
	s_waitcnt lgkmcnt(0)
	s_barrier
	s_setprio 1
	s_waitcnt lgkmcnt(0)
	v_mfma_f32_16x16x32_bf16 v[60:63], v[130:133], v[174:177], v[60:63]
	v_mfma_f32_16x16x32_bf16 v[56:59], v[138:141], v[174:177], v[56:59]
	v_mfma_f32_16x16x32_bf16 v[48:51], v[130:133], v[182:185], v[48:51]
	v_mfma_f32_16x16x32_bf16 v[44:47], v[138:141], v[182:185], v[44:47]
	v_mfma_f32_16x16x32_bf16 v[32:35], v[130:133], v[190:193], v[32:35]
	v_mfma_f32_16x16x32_bf16 v[28:31], v[138:141], v[190:193], v[28:31]
	v_mfma_f32_16x16x32_bf16 v[16:19], v[130:133], v[206:209], v[16:19]
	v_mfma_f32_16x16x32_bf16 v[12:15], v[138:141], v[206:209], v[12:15]
	v_mfma_f32_16x16x32_bf16 v[60:63], v[134:137], v[178:181], v[60:63]
	v_mfma_f32_16x16x32_bf16 v[56:59], v[142:145], v[178:181], v[56:59]
	v_mfma_f32_16x16x32_bf16 v[48:51], v[134:137], v[186:189], v[48:51]
	v_mfma_f32_16x16x32_bf16 v[44:47], v[142:145], v[186:189], v[44:47]
	v_mfma_f32_16x16x32_bf16 v[32:35], v[134:137], v[202:205], v[32:35]
	v_mfma_f32_16x16x32_bf16 v[28:31], v[142:145], v[202:205], v[28:31]
	v_mfma_f32_16x16x32_bf16 v[16:19], v[134:137], v[214:217], v[16:19]
	v_mfma_f32_16x16x32_bf16 v[12:15], v[142:145], v[214:217], v[12:15]
	s_setprio 0
	s_setprio 1
	v_mfma_f32_16x16x32_bf16 v[52:55], v[158:161], v[174:177], v[52:55]
	v_mfma_f32_16x16x32_bf16 v[40:43], v[166:169], v[174:177], v[40:43]
	v_mfma_f32_16x16x32_bf16 v[36:39], v[158:161], v[182:185], v[36:39]
	v_mfma_f32_16x16x32_bf16 v[24:27], v[166:169], v[182:185], v[24:27]
	v_mfma_f32_16x16x32_bf16 v[20:23], v[158:161], v[190:193], v[20:23]
	v_mfma_f32_16x16x32_bf16 v[8:11], v[166:169], v[190:193], v[8:11]
	v_mfma_f32_16x16x32_bf16 v[4:7], v[158:161], v[206:209], v[4:7]
	v_mfma_f32_16x16x32_bf16 v[0:3], v[166:169], v[206:209], v[0:3]
	v_mfma_f32_16x16x32_bf16 v[52:55], v[162:165], v[178:181], v[52:55]
	v_mfma_f32_16x16x32_bf16 v[40:43], v[170:173], v[178:181], v[40:43]
	v_mfma_f32_16x16x32_bf16 v[36:39], v[162:165], v[186:189], v[36:39]
	v_mfma_f32_16x16x32_bf16 v[24:27], v[170:173], v[186:189], v[24:27]
	v_mfma_f32_16x16x32_bf16 v[20:23], v[162:165], v[202:205], v[20:23]
	v_mfma_f32_16x16x32_bf16 v[8:11], v[170:173], v[202:205], v[8:11]
	v_mfma_f32_16x16x32_bf16 v[4:7], v[162:165], v[214:217], v[4:7]
	v_mfma_f32_16x16x32_bf16 v[0:3], v[170:173], v[214:217], v[0:3]
	s_setprio 0
	s_barrier
	s_add_i32 s45, 0, 0x18000
	s_add_i32 s46, 0, 0x1c000
	v_add_u32_e32 v142, s45, v155
	v_add_u32_e32 v170, s46, v155
	ds_read_b128 v[130:133], v142
	ds_read_b128 v[134:137], v142 offset:1024
	ds_read_b128 v[138:141], v142 offset:2048
	ds_read_b128 v[142:145], v142 offset:3072
	ds_read_b128 v[158:161], v170
	ds_read_b128 v[162:165], v170 offset:1024
	ds_read_b128 v[166:169], v170 offset:2048
	ds_read_b128 v[170:173], v170 offset:3072
	s_add_u32 s22, s38, 0x160000
	s_addc_u32 s23, s39, 0
	s_mov_b32 m0, s18
	v_lshl_add_u64 v[218:219], s[22:23], 0, v[96:97]
	ds_read_b128 v[174:177], v157 offset:32768
	ds_read_b128 v[178:181], v157 offset:33792
	ds_read_b128 v[182:185], v157 offset:34816
	ds_read_b128 v[186:189], v157 offset:35840
	ds_read_b128 v[190:193], v157 offset:36864
	ds_read_b128 v[202:205], v157 offset:37888
	ds_read_b128 v[206:209], v157 offset:38912
	ds_read_b128 v[214:217], v157 offset:39936
	global_load_lds_dwordx4 v[218:219], off
	v_lshl_add_u64 v[218:219], s[22:23], 0, v[146:147]
	s_mov_b32 m0, s19
	s_nop 0
	global_load_lds_dwordx4 v[218:219], off
	s_waitcnt vmcnt(8)
	s_waitcnt lgkmcnt(0)
	s_barrier
	s_setprio 1
	s_waitcnt lgkmcnt(0)
	v_mfma_f32_16x16x32_bf16 v[126:129], v[130:133], v[174:177], v[126:129]
	v_mfma_f32_16x16x32_bf16 v[122:125], v[138:141], v[174:177], v[122:125]
	v_mfma_f32_16x16x32_bf16 v[114:117], v[130:133], v[182:185], v[114:117]
	v_mfma_f32_16x16x32_bf16 v[110:113], v[138:141], v[182:185], v[110:113]
	v_mfma_f32_16x16x32_bf16 v[98:101], v[130:133], v[190:193], v[98:101]
	v_mfma_f32_16x16x32_bf16 v[92:95], v[138:141], v[190:193], v[92:95]
	v_mfma_f32_16x16x32_bf16 v[80:83], v[130:133], v[206:209], v[80:83]
	v_mfma_f32_16x16x32_bf16 v[76:79], v[138:141], v[206:209], v[76:79]
	v_mfma_f32_16x16x32_bf16 v[126:129], v[134:137], v[178:181], v[126:129]
	v_mfma_f32_16x16x32_bf16 v[122:125], v[142:145], v[178:181], v[122:125]
	v_mfma_f32_16x16x32_bf16 v[114:117], v[134:137], v[186:189], v[114:117]
	v_mfma_f32_16x16x32_bf16 v[110:113], v[142:145], v[186:189], v[110:113]
	v_mfma_f32_16x16x32_bf16 v[98:101], v[134:137], v[202:205], v[98:101]
	v_mfma_f32_16x16x32_bf16 v[92:95], v[142:145], v[202:205], v[92:95]
	v_mfma_f32_16x16x32_bf16 v[80:83], v[134:137], v[214:217], v[80:83]
	v_mfma_f32_16x16x32_bf16 v[76:79], v[142:145], v[214:217], v[76:79]
	s_setprio 0
	s_setprio 1
	v_mfma_f32_16x16x32_bf16 v[118:121], v[158:161], v[174:177], v[118:121]
	v_mfma_f32_16x16x32_bf16 v[106:109], v[166:169], v[174:177], v[106:109]
	v_mfma_f32_16x16x32_bf16 v[102:105], v[158:161], v[182:185], v[102:105]
	v_mfma_f32_16x16x32_bf16 v[88:91], v[166:169], v[182:185], v[88:91]
	v_mfma_f32_16x16x32_bf16 v[84:87], v[158:161], v[190:193], v[84:87]
	v_mfma_f32_16x16x32_bf16 v[72:75], v[166:169], v[190:193], v[72:75]
	v_mfma_f32_16x16x32_bf16 v[68:71], v[158:161], v[206:209], v[68:71]
	v_mfma_f32_16x16x32_bf16 v[64:67], v[166:169], v[206:209], v[64:67]
	v_mfma_f32_16x16x32_bf16 v[118:121], v[162:165], v[178:181], v[118:121]
	v_mfma_f32_16x16x32_bf16 v[106:109], v[170:173], v[178:181], v[106:109]
	v_mfma_f32_16x16x32_bf16 v[102:105], v[162:165], v[186:189], v[102:105]
	v_mfma_f32_16x16x32_bf16 v[88:91], v[170:173], v[186:189], v[88:91]
	v_mfma_f32_16x16x32_bf16 v[84:87], v[162:165], v[202:205], v[84:87]
	v_mfma_f32_16x16x32_bf16 v[72:75], v[170:173], v[202:205], v[72:75]
	v_mfma_f32_16x16x32_bf16 v[68:71], v[162:165], v[214:217], v[68:71]
	v_mfma_f32_16x16x32_bf16 v[64:67], v[170:173], v[214:217], v[64:67]
	s_setprio 0
	s_barrier
	s_add_i32 s22, s45, s4
	v_lshl_add_u64 v[152:153], v[152:153], 0, s[30:31]
	s_mov_b32 m0, s22
	ds_read_b128 v[174:177], v157 offset:49152
	ds_read_b128 v[178:181], v157 offset:50176
	ds_read_b128 v[182:185], v157 offset:51200
	ds_read_b128 v[186:189], v157 offset:52224
	ds_read_b128 v[190:193], v157 offset:53248
	ds_read_b128 v[202:205], v157 offset:54272
	ds_read_b128 v[206:209], v157 offset:55296
	ds_read_b128 v[214:217], v157 offset:56320
	global_load_lds_dwordx4 v[152:153], off nt
	s_add_i32 m0, s22, 0x2000
	s_add_u32 s22, s34, 0x160080
	v_lshl_add_u64 v[152:153], v[194:195], 0, s[30:31]
	s_addc_u32 s23, s35, 0
	s_add_i32 s34, s46, s4
	global_load_lds_dwordx4 v[152:153], off nt
	v_lshl_add_u64 v[152:153], s[22:23], 0, v[96:97]
	s_mov_b32 m0, s34
	s_nop 0
	global_load_lds_dwordx4 v[152:153], off nt
	v_lshl_add_u64 v[152:153], s[22:23], 0, v[146:147]
	s_add_i32 m0, s34, 0x2000
	s_nop 0
	global_load_lds_dwordx4 v[152:153], off nt
	v_lshl_add_u64 v[152:153], v[198:199], 0, s[30:31]
	s_mov_b32 m0, s20
	s_nop 0
	global_load_lds_dwordx4 v[152:153], off
	v_lshl_add_u64 v[152:153], v[200:201], 0, s[30:31]
	s_mov_b32 m0, s36
	s_nop 0
	global_load_lds_dwordx4 v[152:153], off
	s_waitcnt vmcnt(8)
	s_waitcnt lgkmcnt(0)
	s_barrier
	s_setprio 1
	s_waitcnt lgkmcnt(0)
	v_mfma_f32_16x16x32_bf16 v[60:63], v[130:133], v[174:177], v[60:63]
	v_mfma_f32_16x16x32_bf16 v[56:59], v[138:141], v[174:177], v[56:59]
	v_mfma_f32_16x16x32_bf16 v[48:51], v[130:133], v[182:185], v[48:51]
	v_mfma_f32_16x16x32_bf16 v[44:47], v[138:141], v[182:185], v[44:47]
	v_mfma_f32_16x16x32_bf16 v[32:35], v[130:133], v[190:193], v[32:35]
	v_mfma_f32_16x16x32_bf16 v[28:31], v[138:141], v[190:193], v[28:31]
	v_mfma_f32_16x16x32_bf16 v[16:19], v[130:133], v[206:209], v[16:19]
	v_mfma_f32_16x16x32_bf16 v[12:15], v[138:141], v[206:209], v[12:15]
	v_mfma_f32_16x16x32_bf16 v[60:63], v[134:137], v[178:181], v[60:63]
	v_mfma_f32_16x16x32_bf16 v[56:59], v[142:145], v[178:181], v[56:59]
	v_mfma_f32_16x16x32_bf16 v[48:51], v[134:137], v[186:189], v[48:51]
	v_mfma_f32_16x16x32_bf16 v[44:47], v[142:145], v[186:189], v[44:47]
	v_mfma_f32_16x16x32_bf16 v[32:35], v[134:137], v[202:205], v[32:35]
	v_mfma_f32_16x16x32_bf16 v[28:31], v[142:145], v[202:205], v[28:31]
	v_mfma_f32_16x16x32_bf16 v[16:19], v[134:137], v[214:217], v[16:19]
	v_mfma_f32_16x16x32_bf16 v[12:15], v[142:145], v[214:217], v[12:15]
	s_setprio 0
	s_setprio 1
	v_mfma_f32_16x16x32_bf16 v[52:55], v[158:161], v[174:177], v[52:55]
	v_mfma_f32_16x16x32_bf16 v[40:43], v[166:169], v[174:177], v[40:43]
	v_mfma_f32_16x16x32_bf16 v[36:39], v[158:161], v[182:185], v[36:39]
	v_mfma_f32_16x16x32_bf16 v[24:27], v[166:169], v[182:185], v[24:27]
	v_mfma_f32_16x16x32_bf16 v[20:23], v[158:161], v[190:193], v[20:23]
	v_mfma_f32_16x16x32_bf16 v[8:11], v[166:169], v[190:193], v[8:11]
	v_mfma_f32_16x16x32_bf16 v[4:7], v[158:161], v[206:209], v[4:7]
	v_mfma_f32_16x16x32_bf16 v[0:3], v[166:169], v[206:209], v[0:3]
	v_mfma_f32_16x16x32_bf16 v[52:55], v[162:165], v[178:181], v[52:55]
	v_mfma_f32_16x16x32_bf16 v[40:43], v[170:173], v[178:181], v[40:43]
	v_mfma_f32_16x16x32_bf16 v[36:39], v[162:165], v[186:189], v[36:39]
	v_mfma_f32_16x16x32_bf16 v[24:27], v[170:173], v[186:189], v[24:27]
	v_mfma_f32_16x16x32_bf16 v[20:23], v[162:165], v[202:205], v[20:23]
	v_mfma_f32_16x16x32_bf16 v[8:11], v[170:173], v[202:205], v[8:11]
	v_mfma_f32_16x16x32_bf16 v[4:7], v[162:165], v[214:217], v[4:7]
	v_mfma_f32_16x16x32_bf16 v[0:3], v[170:173], v[214:217], v[0:3]
	s_setprio 0
	s_barrier
	s_add_i32 s6, s6, 2
	s_add_u32 s2, s2, 0x100
	s_addc_u32 s3, s3, 0
	s_cmpk_gt_u32 s6, 0x55
	s_mov_b64 s[22:23], s[24:25]
	s_cbranch_scc0 .LBB0_1413
	s_and_b64 vcc, exec, s[10:11]
	s_cbranch_vccz .LBB0_1416
	s_barrier
